# attention loops rotated: next tile K fragments are read from LDS during the PV phase, so QK MFMAs start at the step top and the barrier sits mid-QK
# speedup vs baseline: 1.0409x; 1.0124x over previous
; #define MFMA(a, b, c) __builtin_amdgcn_mfma_f32_32x32x16_bf16((a), (b), (c), 0, 0, 0)
; DI int crow(int i, int h) { return (i & 3) + 8 * (i >> 2) + 4 * h; }
; DI int swap23(int r) { return (r & 0x13) | ((r & 4) << 1) | ((r & 8) >> 1); }
;   DI void qk(int buf, f32x16 (&s)[2]) {
;     const u16* kb = sK + buf * KBUF + sr * KP + h * 8;
; #pragma unroll
;     for (int kb2 = 0; kb2 < 2; ++kb2)
; #pragma unroll
;       for (int i = 0; i < 16; ++i) s[kb2][i] = 0.f;
; #pragma unroll
;     for (int ks = 0; ks < NKS; ++ks)
; #pragma unroll
;       for (int kb2 = 0; kb2 < 2; ++kb2) {
;         const bf16x8 a = *(const bf16x8*)(kb + kb2 * 32 * KP + ks * 16);
;         s[kb2] = MFMA(a, qf[ks], s[kb2]);
;       }
;     s[0] = MFMA(kone, qm, s[0]);
;     s[1] = MFMA(kone, qm, s[1]);
;   }
;   template <int PAR>
;   DI void step(int t, f32x16 (&cur)[2], f32x16 (&nxt)[2]) {
;     if (t + 1 < nt) sstore_k(PAR ^ 1);
;     if (t > 0) sstore_v(PAR);
;     __syncthreads();
;     if (t + 1 < nt) qk(PAR ^ 1, nxt);
;     float mx = fmaxf(cur[0][0], cur[1][0]);
; #pragma unroll
;     for (int i = 1; i < 16; ++i) mx = fmaxf(fmaxf(cur[0][i], cur[1][i]), mx);
;     if (__builtin_amdgcn_ballot_w64(mx > ATT_THR) != 0ull) {
; template <int DQK>
; DI void attn_item(const u16* __restrict__ Qb, int qpitch, const u16* __restrict__ Kb, int kpitch, const u16* __restrict__ KPEb,
;                   const u16* __restrict__ Vt, float* __restrict__ ssq, int rowq0, int rowk0, int nt, char* smem, int tid, bool dry) {
;     ...
;   c.gload_k(0); c.gload_v(0);
;   __syncthreads();
;   c.sstore_k(0); c.sstore_v(0);
;   if (nt > 1) c.gload_k(1);
;   __syncthreads();
;   c.qk(0, sa);
; #pragma unroll
;   for (int i = 0; i < 16; ++i) {
;     sa[0][i] = -1e30f;
;     if (swap23(crow(i, h)) < 16) sa[1][i] = -1e30f;
;   }
;   int t = 0;
;   for (; t + 1 < nt; t += 2) {
;     c.template step<0>(t, sa, sb);
;     c.template step<1>(t + 1, sb, sa);
;   }
;   if (t < nt) c.template step<0>(t, sa, sb);
.Lg_entry:
	v_mov_b32_e32 v169, 0
	v_mov_b32_e32 v170, 0
	v_mov_b32_e32 v171, 0
	v_mov_b32_e32 v182, 0
	v_mov_b32_e32 v183, 0
	s_waitcnt vmcnt(2)
	ds_write_b128 v248, v[152:155] offset:9216
	ds_write_b128 v249, v[156:159] offset:9216
	s_sub_i32 s0, s46, 64
	s_ashr_i32 s1, s0, 31
	s_lshl_b64 s[0:1], s[0:1], 8
	s_add_u32 s0, s26, s0
	s_addc_u32 s1, s27, s1
	v_lshl_add_u64 v[214:215], v[184:185], 1, s[0:1]
	v_lshl_add_u64 v[216:217], v[186:187], 1, s[0:1]
	s_mov_b32 s20, 0x4000
	s_mov_b32 s21, 0
	global_load_dwordx4 v[152:155], v[214:215], off
	global_load_dwordx4 v[156:159], v[216:217], off
	v_lshl_add_u64 v[214:215], v[214:215], 0, s[20:21]
	v_lshl_add_u64 v[216:217], v[216:217], 0, s[20:21]
.Lg_entryK:
	s_waitcnt lgkmcnt(0)
	s_barrier
	ds_read_b128 v[96:99], v195 offset:9216
	ds_read_b128 v[100:103], v195 offset:13824
	ds_read_b128 v[104:107], v195 offset:9248
	ds_read_b128 v[108:111], v195 offset:13856
	ds_read_b128 v[112:115], v195 offset:9280
	ds_read_b128 v[116:119], v195 offset:13888
	ds_read_b128 v[120:123], v195 offset:9312
	ds_read_b128 v[124:127], v195 offset:13920
	v_max3_f32 v128, v48, v32, v49
	v_max3_f32 v172, v33, v50, v34
	v_max3_f32 v128, v51, v35, v128
	v_max3_f32 v172, v52, v36, v172
	v_max3_f32 v128, v53, v37, v128
	v_max3_f32 v172, v54, v38, v172
	v_max3_f32 v128, v55, v39, v128
	v_max3_f32 v172, v56, v40, v172
	v_max3_f32 v128, v57, v41, v128
	v_max3_f32 v172, v58, v42, v172
	v_max3_f32 v128, v59, v43, v128
	v_max3_f32 v172, v60, v44, v172
	v_max3_f32 v128, v61, v45, v128
	v_max3_f32 v172, v62, v46, v172
	v_max3_f32 v128, v63, v47, v128
	v_max_f32_e32 v128, v128, v172
	v_and_b32_e32 v179, 0x7fff, v168
	v_cmp_ne_u32_e32 vcc, 0, v179
	s_cbranch_vccnz .LBB0_238
.Lgf_top:
	s_waitcnt vmcnt(0)
	ds_write_b128 v248, v[152:155]
	ds_write_b128 v249, v[156:159]
	ds_write_b128 v194, v[160:163] offset:18432
	ds_write_b128 v196, v[164:167] offset:18432
	v_cmp_lt_f32_e32 vcc, s65, v128
	s_cbranch_vccnz .Lgf_rareA
.Lgf_rareA_ret:
	s_add_i32 s0, s45, -1
	s_cmp_ge_u32 s0, s19
	s_cselect_b64 s[14:15], -1, 0
	s_cmp_ge_u32 s45, s19
	s_cbranch_scc1 .Lgf_skipKA
	global_load_dwordx4 v[152:155], v[214:215], off
	global_load_dwordx4 v[156:159], v[216:217], off
	v_lshl_add_u64 v[214:215], v[214:215], 0, s[20:21]
	v_lshl_add_u64 v[216:217], v[216:217], 0, s[20:21]
; #define MFMA(a, b, c) __builtin_amdgcn_mfma_f32_32x32x16_bf16((a), (b), (c), 0, 0, 0)
; DI unsigned pack2(float a, float b) { f32x2v f = {a, b}; bf16x2v v = __builtin_convertvector(f, bf16x2v); return __builtin_bit_cast(unsigned, v); }
; DI float xhalf(float v) { return __shfl_xor(v, 32); }
;   template <int PAR>
;   DI void step(int t, f32x16 (&cur)[2], f32x16 (&nxt)[2]) {
;     if (t + 1 < nt) sstore_k(PAR ^ 1);
;     if (t > 0) sstore_v(PAR);
;     __syncthreads();
;     if (t + 1 < nt) qk(PAR ^ 1, nxt);
;     float mx = fmaxf(cur[0][0], cur[1][0]);
; #pragma unroll
;     for (int i = 1; i < 16; ++i) mx = fmaxf(fmaxf(cur[0][i], cur[1][i]), mx);
;     if (__builtin_amdgcn_ballot_w64(mx > ATT_THR) != 0ull) {
;       asm volatile("" ::: "memory");
;       mx = fmaxf(mx, xhalf(mx));
;       const float want = mref + fmaxf(mx, 0.f);
;       const float mn = __uint_as_float(pack2(want, 0.f) << 16);
;       const float d = mn - mref;
;       const float alpha = __builtin_amdgcn_exp2f(-d);
;       mref = mn;
;       l *= alpha;
; #pragma unroll
;       for (int a = 0; a < 2; ++a)
; #pragma unroll
;         for (int i = 0; i < 16; ++i) { o[a][i] *= alpha; cur[a][i] -= d; nxt[a][i] -= d; }
;       u32x4 q4 = {h == 0 ? (pack2(-mn, 0.f) & 0xffffu) : 0u, 0u, 0u, 0u};
;       qm = __builtin_bit_cast(bf16x8, q4);
;     }
;     float psum = 0.f;
; #pragma unroll
;     for (int kb2 = 0; kb2 < 2; ++kb2)
; #pragma unroll
;       for (int i = 0; i < 16; ++i) { const float pv = __builtin_amdgcn_exp2f(cur[kb2][i]); cur[kb2][i] = pv; psum += pv; }
;     l += psum;
;     if (t + 2 < nt) gload_k(t + 2);
;     if (t + 1 < nt) gload_v(t + 1);
;     const u16* vb = sV + PAR * VBUF + r * GP + h * 8;
; #pragma unroll
;     for (int kb2 = 0; kb2 < 2; ++kb2)
; #pragma unroll
;       for (int s2 = 0; s2 < 2; ++s2) {
;         u32x4 pk = {pack2(cur[kb2][8 * s2], cur[kb2][8 * s2 + 1]), pack2(cur[kb2][8 * s2 + 2], cur[kb2][8 * s2 + 3]),
;                     pack2(cur[kb2][8 * s2 + 4], cur[kb2][8 * s2 + 5]), pack2(cur[kb2][8 * s2 + 6], cur[kb2][8 * s2 + 7])};
;         const bf16x8 pf = __builtin_bit_cast(bf16x8, pk);
; #pragma unroll
;         for (int db = 0; db < 2; ++db) {
;           const bf16x8 a = *(const bf16x8*)(vb + db * 32 * GP + kb2 * 32 + s2 * 16);
;           o[db] = MFMA(a, pf, o[db]);
;         }
;       }
;   }
.Lgf_skipKA:
	global_load_dwordx4 v[160:163], v[130:131], off offset:-128
	global_load_dwordx4 v[164:167], v[180:181], off offset:-128
	v_exp_f32_e32 v48, v48
	v_exp_f32_e32 v49, v49
	v_exp_f32_e32 v50, v50
	v_add_f32_e32 v182, v48, v182
	v_exp_f32_e32 v51, v51
	v_add_f32_e32 v183, v49, v183
	v_exp_f32_e32 v52, v52
	v_add_f32_e32 v182, v50, v182
	s_waitcnt lgkmcnt(11)
	v_mfma_f32_32x32x16_bf16 v[80:95], v[96:99], v[136:139], 0
	v_exp_f32_e32 v53, v53
	v_add_f32_e32 v183, v51, v183
	v_exp_f32_e32 v54, v54
	v_add_f32_e32 v182, v52, v182
	v_exp_f32_e32 v55, v55
	v_add_f32_e32 v183, v53, v183
	s_waitcnt lgkmcnt(10)
	v_mfma_f32_32x32x16_bf16 v[64:79], v[100:103], v[136:139], 0
	v_cvt_pk_bf16_f32 v48, v48, v49
	v_add_f32_e32 v182, v54, v182
	v_cvt_pk_bf16_f32 v49, v50, v51
	v_add_f32_e32 v183, v55, v183
	v_cvt_pk_bf16_f32 v50, v52, v53
	v_cvt_pk_bf16_f32 v51, v54, v55
	s_waitcnt lgkmcnt(9)
	v_mfma_f32_32x32x16_bf16 v[80:95], v[104:107], v[140:143], v[80:95]
	v_exp_f32_e32 v56, v56
	v_exp_f32_e32 v57, v57
	v_exp_f32_e32 v58, v58
	v_add_f32_e32 v182, v56, v182
	v_exp_f32_e32 v59, v59
	v_add_f32_e32 v183, v57, v183
	s_waitcnt lgkmcnt(8)
	v_mfma_f32_32x32x16_bf16 v[64:79], v[108:111], v[140:143], v[64:79]
	v_exp_f32_e32 v60, v60
	v_add_f32_e32 v182, v58, v182
	v_exp_f32_e32 v61, v61
	v_add_f32_e32 v183, v59, v183
	v_exp_f32_e32 v62, v62
	v_add_f32_e32 v182, v60, v182
	s_waitcnt lgkmcnt(0)
	s_barrier
	ds_read_b128 v[96:99], v197 offset:18432
	ds_read_b128 v[100:103], v197 offset:23040
	ds_read_b128 v[104:107], v197 offset:18464
	ds_read_b128 v[108:111], v197 offset:23072
	v_mfma_f32_32x32x16_bf16 v[80:95], v[112:115], v[144:147], v[80:95]
	ds_read_b128 v[112:115], v197 offset:18496
	v_exp_f32_e32 v63, v63
	v_add_f32_e32 v183, v61, v183
	v_cvt_pk_bf16_f32 v56, v56, v57
	v_add_f32_e32 v182, v62, v182
	v_cvt_pk_bf16_f32 v57, v58, v59
	v_add_f32_e32 v183, v63, v183
	v_mfma_f32_32x32x16_bf16 v[64:79], v[116:119], v[144:147], v[64:79]
	ds_read_b128 v[116:119], v197 offset:23104
	v_cvt_pk_bf16_f32 v58, v60, v61
	v_cvt_pk_bf16_f32 v59, v62, v63
	v_exp_f32_e32 v32, v32
	v_exp_f32_e32 v33, v33
	v_exp_f32_e32 v34, v34
	v_add_f32_e32 v182, v32, v182
	v_mfma_f32_32x32x16_bf16 v[80:95], v[120:123], v[148:151], v[80:95]
	ds_read_b128 v[120:123], v197 offset:18528
	v_exp_f32_e32 v35, v35
	v_add_f32_e32 v183, v33, v183
	v_exp_f32_e32 v36, v36
	v_add_f32_e32 v182, v34, v182
	v_exp_f32_e32 v37, v37
	v_add_f32_e32 v183, v35, v183
	v_mfma_f32_32x32x16_bf16 v[64:79], v[124:127], v[148:151], v[64:79]
	ds_read_b128 v[124:127], v197 offset:23136
	v_exp_f32_e32 v38, v38
	v_add_f32_e32 v182, v36, v182
	v_exp_f32_e32 v39, v39
	v_add_f32_e32 v183, v37, v183
	v_cvt_pk_bf16_f32 v32, v32, v33
	v_add_f32_e32 v182, v38, v182
	s_waitcnt lgkmcnt(7)
	v_mfma_f32_32x32x16_bf16 v[16:31], v[96:99], v[48:51], v[16:31]
	ds_read_b128 v[96:99], v195
	v_cvt_pk_bf16_f32 v33, v34, v35
	v_add_f32_e32 v183, v39, v183
	v_cvt_pk_bf16_f32 v34, v36, v37
	v_cvt_pk_bf16_f32 v35, v38, v39
	v_exp_f32_e32 v40, v40
	s_waitcnt lgkmcnt(7)
	v_mfma_f32_32x32x16_bf16 v[0:15], v[100:103], v[48:51], v[0:15]
	ds_read_b128 v[100:103], v195 offset:4608
	v_exp_f32_e32 v41, v41
	v_exp_f32_e32 v42, v42
	v_add_f32_e32 v182, v40, v182
	v_exp_f32_e32 v43, v43
	v_add_f32_e32 v183, v41, v183
	s_waitcnt lgkmcnt(7)
	v_mfma_f32_32x32x16_bf16 v[16:31], v[104:107], v[56:59], v[16:31]
	ds_read_b128 v[104:107], v195 offset:32
	v_exp_f32_e32 v44, v44
	v_add_f32_e32 v182, v42, v182
	v_exp_f32_e32 v45, v45
	v_add_f32_e32 v183, v43, v183
	v_exp_f32_e32 v46, v46
	s_waitcnt lgkmcnt(7)
	v_mfma_f32_32x32x16_bf16 v[0:15], v[108:111], v[56:59], v[0:15]
	ds_read_b128 v[108:111], v195 offset:4640
	v_add_f32_e32 v182, v44, v182
	v_exp_f32_e32 v47, v47
	v_add_f32_e32 v183, v45, v183
	v_cvt_pk_bf16_f32 v40, v40, v41
	v_add_f32_e32 v182, v46, v182
	s_waitcnt lgkmcnt(7)
	v_mfma_f32_32x32x16_bf16 v[16:31], v[112:115], v[32:35], v[16:31]
	ds_read_b128 v[112:115], v195 offset:64
	v_cvt_pk_bf16_f32 v41, v42, v43
	v_add_f32_e32 v183, v47, v183
	v_cvt_pk_bf16_f32 v42, v44, v45
	v_cvt_pk_bf16_f32 v43, v46, v47
	v_max3_f32 v128, v80, v64, v81
	s_waitcnt lgkmcnt(7)
	v_mfma_f32_32x32x16_bf16 v[0:15], v[116:119], v[32:35], v[0:15]
	ds_read_b128 v[116:119], v195 offset:4672
	v_max3_f32 v172, v65, v82, v66
	v_max3_f32 v128, v83, v67, v128
	v_max3_f32 v172, v84, v68, v172
	v_max3_f32 v128, v85, v69, v128
	v_max3_f32 v172, v86, v70, v172
	s_waitcnt lgkmcnt(7)
	v_mfma_f32_32x32x16_bf16 v[16:31], v[120:123], v[40:43], v[16:31]
	ds_read_b128 v[120:123], v195 offset:96
	v_max3_f32 v128, v87, v71, v128
	v_max3_f32 v172, v88, v72, v172
	v_max3_f32 v128, v89, v73, v128
	v_max3_f32 v172, v90, v74, v172
	v_max3_f32 v128, v91, v75, v128
	s_waitcnt lgkmcnt(7)
	v_mfma_f32_32x32x16_bf16 v[0:15], v[124:127], v[40:43], v[0:15]
	ds_read_b128 v[124:127], v195 offset:4704
	v_max3_f32 v172, v92, v76, v172
	v_max3_f32 v128, v93, v77, v128
	v_max3_f32 v172, v94, v78, v172
	v_max3_f32 v128, v95, v79, v128
	v_max_f32_e32 v128, v128, v172
	s_waitcnt vmcnt(0)
	ds_write_b128 v248, v[152:155] offset:9216
	ds_write_b128 v249, v[156:159] offset:9216
	ds_write_b128 v194, v[160:163] offset:27648
	ds_write_b128 v196, v[164:167] offset:27648
	v_cmp_lt_f32_e32 vcc, s65, v128
	s_cbranch_vccnz .Lgf_rareB
.Lgf_rareB_ret:
	s_add_i32 s0, s45, 1
	s_cmp_ge_u32 s0, s19
	s_cbranch_scc1 .Lgf_skipKB
	global_load_dwordx4 v[152:155], v[214:215], off
	global_load_dwordx4 v[156:159], v[216:217], off
	v_lshl_add_u64 v[214:215], v[214:215], 0, s[20:21]
	v_lshl_add_u64 v[216:217], v[216:217], 0, s[20:21]

; #define MFMA(a, b, c) __builtin_amdgcn_mfma_f32_32x32x16_bf16((a), (b), (c), 0, 0, 0)
; DI unsigned pack2(float a, float b) { f32x2v f = {a, b}; bf16x2v v = __builtin_convertvector(f, bf16x2v); return __builtin_bit_cast(unsigned, v); }
; DI float xhalf(float v) { return __shfl_xor(v, 32); }
;   template <int PAR>
;   DI void step(int t, f32x16 (&cur)[2], f32x16 (&nxt)[2]) {
;     if (t + 1 < nt) sstore_k(PAR ^ 1);
;     if (t > 0) sstore_v(PAR);
;     __syncthreads();
;     if (t + 1 < nt) qk(PAR ^ 1, nxt);
;     float mx = fmaxf(cur[0][0], cur[1][0]);
; #pragma unroll
;     for (int i = 1; i < 16; ++i) mx = fmaxf(fmaxf(cur[0][i], cur[1][i]), mx);
;     if (__builtin_amdgcn_ballot_w64(mx > ATT_THR) != 0ull) {
;       asm volatile("" ::: "memory");
;       mx = fmaxf(mx, xhalf(mx));
;       const float want = mref + fmaxf(mx, 0.f);
;       const float mn = __uint_as_float(pack2(want, 0.f) << 16);
;       const float d = mn - mref;
;       const float alpha = __builtin_amdgcn_exp2f(-d);
;       mref = mn;
;       l *= alpha;
; #pragma unroll
;       for (int a = 0; a < 2; ++a)
; #pragma unroll
;         for (int i = 0; i < 16; ++i) { o[a][i] *= alpha; cur[a][i] -= d; nxt[a][i] -= d; }
;       u32x4 q4 = {h == 0 ? (pack2(-mn, 0.f) & 0xffffu) : 0u, 0u, 0u, 0u};
;       qm = __builtin_bit_cast(bf16x8, q4);
;     }
;     float psum = 0.f;
; #pragma unroll
;     for (int kb2 = 0; kb2 < 2; ++kb2)
; #pragma unroll
;       for (int i = 0; i < 16; ++i) { const float pv = __builtin_amdgcn_exp2f(cur[kb2][i]); cur[kb2][i] = pv; psum += pv; }
;     l += psum;
;     if (t + 2 < nt) gload_k(t + 2);
;     if (t + 1 < nt) gload_v(t + 1);
;     const u16* vb = sV + PAR * VBUF + r * GP + h * 8;
; #pragma unroll
;     for (int kb2 = 0; kb2 < 2; ++kb2)
; #pragma unroll
;       for (int s2 = 0; s2 < 2; ++s2) {
;         u32x4 pk = {pack2(cur[kb2][8 * s2], cur[kb2][8 * s2 + 1]), pack2(cur[kb2][8 * s2 + 2], cur[kb2][8 * s2 + 3]),
;                     pack2(cur[kb2][8 * s2 + 4], cur[kb2][8 * s2 + 5]), pack2(cur[kb2][8 * s2 + 6], cur[kb2][8 * s2 + 7])};
;         const bf16x8 pf = __builtin_bit_cast(bf16x8, pk);
; #pragma unroll
;         for (int db = 0; db < 2; ++db) {
;           const bf16x8 a = *(const bf16x8*)(vb + db * 32 * GP + kb2 * 32 + s2 * 16);
;           o[db] = MFMA(a, pf, o[db]);
;         }
;       }
;   }
.Lgf_skipVB:
	v_exp_f32_e32 v80, v80
	v_exp_f32_e32 v81, v81
	v_exp_f32_e32 v82, v82
	v_add_f32_e32 v182, v80, v182
	v_exp_f32_e32 v83, v83
	v_add_f32_e32 v183, v81, v183
	v_exp_f32_e32 v84, v84
	v_add_f32_e32 v182, v82, v182
	s_waitcnt lgkmcnt(11)
	v_mfma_f32_32x32x16_bf16 v[48:63], v[96:99], v[136:139], 0
	v_exp_f32_e32 v85, v85
	v_add_f32_e32 v183, v83, v183
	v_exp_f32_e32 v86, v86
	v_add_f32_e32 v182, v84, v182
	v_exp_f32_e32 v87, v87
	v_add_f32_e32 v183, v85, v183
	s_waitcnt lgkmcnt(10)
	v_mfma_f32_32x32x16_bf16 v[32:47], v[100:103], v[136:139], 0
	v_cvt_pk_bf16_f32 v80, v80, v81
	v_add_f32_e32 v182, v86, v182
	v_cvt_pk_bf16_f32 v81, v82, v83
	v_add_f32_e32 v183, v87, v183
	v_cvt_pk_bf16_f32 v82, v84, v85
	v_cvt_pk_bf16_f32 v83, v86, v87
	s_waitcnt lgkmcnt(9)
	v_mfma_f32_32x32x16_bf16 v[48:63], v[104:107], v[140:143], v[48:63]
	v_exp_f32_e32 v88, v88
	v_exp_f32_e32 v89, v89
	v_exp_f32_e32 v90, v90
	v_add_f32_e32 v182, v88, v182
	v_exp_f32_e32 v91, v91
	v_add_f32_e32 v183, v89, v183
	s_waitcnt lgkmcnt(8)
	v_mfma_f32_32x32x16_bf16 v[32:47], v[108:111], v[140:143], v[32:47]
	v_exp_f32_e32 v92, v92
	v_add_f32_e32 v182, v90, v182
	v_exp_f32_e32 v93, v93
	v_add_f32_e32 v183, v91, v183
	v_exp_f32_e32 v94, v94
	v_add_f32_e32 v182, v92, v182
	s_waitcnt lgkmcnt(0)
	s_barrier
	ds_read_b128 v[96:99], v197 offset:27648
	ds_read_b128 v[100:103], v197 offset:32256
	ds_read_b128 v[104:107], v197 offset:27680
	ds_read_b128 v[108:111], v197 offset:32288
	v_mfma_f32_32x32x16_bf16 v[48:63], v[112:115], v[144:147], v[48:63]
	ds_read_b128 v[112:115], v197 offset:27712
	v_exp_f32_e32 v95, v95
	v_add_f32_e32 v183, v93, v183
	v_cvt_pk_bf16_f32 v88, v88, v89
	v_add_f32_e32 v182, v94, v182
	v_cvt_pk_bf16_f32 v89, v90, v91
	v_add_f32_e32 v183, v95, v183
	v_mfma_f32_32x32x16_bf16 v[32:47], v[116:119], v[144:147], v[32:47]
	ds_read_b128 v[116:119], v197 offset:32320
	v_cvt_pk_bf16_f32 v90, v92, v93
	v_cvt_pk_bf16_f32 v91, v94, v95
	v_exp_f32_e32 v64, v64
	v_exp_f32_e32 v65, v65
	v_exp_f32_e32 v66, v66
	v_add_f32_e32 v182, v64, v182
	v_mfma_f32_32x32x16_bf16 v[48:63], v[120:123], v[148:151], v[48:63]
	ds_read_b128 v[120:123], v197 offset:27744
	v_exp_f32_e32 v67, v67
	v_add_f32_e32 v183, v65, v183
	v_exp_f32_e32 v68, v68
	v_add_f32_e32 v182, v66, v182
	v_exp_f32_e32 v69, v69
	v_add_f32_e32 v183, v67, v183
	v_mfma_f32_32x32x16_bf16 v[32:47], v[124:127], v[148:151], v[32:47]
	ds_read_b128 v[124:127], v197 offset:32352
	v_exp_f32_e32 v70, v70
	v_add_f32_e32 v182, v68, v182
	v_exp_f32_e32 v71, v71
	v_add_f32_e32 v183, v69, v183
	v_cvt_pk_bf16_f32 v64, v64, v65
	v_add_f32_e32 v182, v70, v182
	s_waitcnt lgkmcnt(7)
	v_mfma_f32_32x32x16_bf16 v[16:31], v[96:99], v[80:83], v[16:31]
	ds_read_b128 v[96:99], v195 offset:9216
	v_cvt_pk_bf16_f32 v65, v66, v67
	v_add_f32_e32 v183, v71, v183
	v_cvt_pk_bf16_f32 v66, v68, v69
	v_cvt_pk_bf16_f32 v67, v70, v71
	v_exp_f32_e32 v72, v72
	s_waitcnt lgkmcnt(7)
	v_mfma_f32_32x32x16_bf16 v[0:15], v[100:103], v[80:83], v[0:15]
	ds_read_b128 v[100:103], v195 offset:13824
	v_exp_f32_e32 v73, v73
	v_exp_f32_e32 v74, v74
	v_add_f32_e32 v182, v72, v182
	v_exp_f32_e32 v75, v75
	v_add_f32_e32 v183, v73, v183
	s_waitcnt lgkmcnt(7)
	v_mfma_f32_32x32x16_bf16 v[16:31], v[104:107], v[88:91], v[16:31]
	ds_read_b128 v[104:107], v195 offset:9248
	v_exp_f32_e32 v76, v76
	v_add_f32_e32 v182, v74, v182
	v_exp_f32_e32 v77, v77
	v_add_f32_e32 v183, v75, v183
	v_exp_f32_e32 v78, v78
	s_waitcnt lgkmcnt(7)
	v_mfma_f32_32x32x16_bf16 v[0:15], v[108:111], v[88:91], v[0:15]
	ds_read_b128 v[108:111], v195 offset:13856
	v_add_f32_e32 v182, v76, v182
	v_exp_f32_e32 v79, v79
	v_add_f32_e32 v183, v77, v183
	v_cvt_pk_bf16_f32 v72, v72, v73
	v_add_f32_e32 v182, v78, v182
	s_waitcnt lgkmcnt(7)
	v_mfma_f32_32x32x16_bf16 v[16:31], v[112:115], v[64:67], v[16:31]
	ds_read_b128 v[112:115], v195 offset:9280
	v_cvt_pk_bf16_f32 v73, v74, v75
	v_add_f32_e32 v183, v79, v183
	v_cvt_pk_bf16_f32 v74, v76, v77
	v_cvt_pk_bf16_f32 v75, v78, v79
	v_max3_f32 v128, v48, v32, v49
	s_waitcnt lgkmcnt(7)
	v_mfma_f32_32x32x16_bf16 v[0:15], v[116:119], v[64:67], v[0:15]
	ds_read_b128 v[116:119], v195 offset:13888
	v_max3_f32 v172, v33, v50, v34
	v_max3_f32 v128, v51, v35, v128
	v_max3_f32 v172, v52, v36, v172
	v_max3_f32 v128, v53, v37, v128
	v_max3_f32 v172, v54, v38, v172
	s_waitcnt lgkmcnt(7)
	v_mfma_f32_32x32x16_bf16 v[16:31], v[120:123], v[72:75], v[16:31]
	ds_read_b128 v[120:123], v195 offset:9312
	v_max3_f32 v128, v55, v39, v128
	v_max3_f32 v172, v56, v40, v172
	v_max3_f32 v128, v57, v41, v128
	v_max3_f32 v172, v58, v42, v172
	v_max3_f32 v128, v59, v43, v128
	s_waitcnt lgkmcnt(7)
	v_mfma_f32_32x32x16_bf16 v[0:15], v[124:127], v[72:75], v[0:15]
	ds_read_b128 v[124:127], v195 offset:13920
	v_max3_f32 v172, v60, v44, v172
	v_max3_f32 v128, v61, v45, v128
	v_max3_f32 v172, v62, v46, v172
	v_max3_f32 v128, v63, v47, v128
	v_max_f32_e32 v128, v128, v172
	v_lshl_add_u64 v[130:131], v[130:131], 0, s[84:85]
	v_lshl_add_u64 v[180:181], v[180:181], 0, s[84:85]
	s_mov_b32 s0, s45
	s_add_i32 s45, s45, 2
	s_cmp_lt_u32 s0, s19
	s_cbranch_scc1 .Lgf_top
	s_branch .Lg_fold

; #define MFMA(a, b, c) __builtin_amdgcn_mfma_f32_32x32x16_bf16((a), (b), (c), 0, 0, 0)
; DI unsigned pack2(float a, float b) { f32x2v f = {a, b}; bf16x2v v = __builtin_convertvector(f, bf16x2v); return __builtin_bit_cast(unsigned, v); }
; DI float xhalf(float v) { return __shfl_xor(v, 32); }
;   template <int PAR>
;   DI void step(int t, f32x16 (&cur)[2], f32x16 (&nxt)[2]) {
;     if (t + 1 < nt) sstore_k(PAR ^ 1);
;     if (t > 0) sstore_v(PAR);
;     __syncthreads();
;     if (t + 1 < nt) qk(PAR ^ 1, nxt);
;     float mx = fmaxf(cur[0][0], cur[1][0]);
; #pragma unroll
;     for (int i = 1; i < 16; ++i) mx = fmaxf(fmaxf(cur[0][i], cur[1][i]), mx);
;     if (__builtin_amdgcn_ballot_w64(mx > ATT_THR) != 0ull) {
;       asm volatile("" ::: "memory");
;       mx = fmaxf(mx, xhalf(mx));
;       const float want = mref + fmaxf(mx, 0.f);
;       const float mn = __uint_as_float(pack2(want, 0.f) << 16);
;       const float d = mn - mref;
;       const float alpha = __builtin_amdgcn_exp2f(-d);
;       mref = mn;
;       l *= alpha;
; #pragma unroll
;       for (int a = 0; a < 2; ++a)
; #pragma unroll
;         for (int i = 0; i < 16; ++i) { o[a][i] *= alpha; cur[a][i] -= d; nxt[a][i] -= d; }
;       u32x4 q4 = {h == 0 ? (pack2(-mn, 0.f) & 0xffffu) : 0u, 0u, 0u, 0u};
;       qm = __builtin_bit_cast(bf16x8, q4);
;     }
;     float psum = 0.f;
; #pragma unroll
;     for (int kb2 = 0; kb2 < 2; ++kb2)
; #pragma unroll
;       for (int i = 0; i < 16; ++i) { const float pv = __builtin_amdgcn_exp2f(cur[kb2][i]); cur[kb2][i] = pv; psum += pv; }
;     l += psum;
;     if (t + 2 < nt) gload_k(t + 2);
;     if (t + 1 < nt) gload_v(t + 1);
;     const u16* vb = sV + PAR * VBUF + r * GP + h * 8;
; #pragma unroll
;     for (int kb2 = 0; kb2 < 2; ++kb2)
; #pragma unroll
;       for (int s2 = 0; s2 < 2; ++s2) {
;         u32x4 pk = {pack2(cur[kb2][8 * s2], cur[kb2][8 * s2 + 1]), pack2(cur[kb2][8 * s2 + 2], cur[kb2][8 * s2 + 3]),
;                     pack2(cur[kb2][8 * s2 + 4], cur[kb2][8 * s2 + 5]), pack2(cur[kb2][8 * s2 + 6], cur[kb2][8 * s2 + 7])};
;         const bf16x8 pf = __builtin_bit_cast(bf16x8, pk);
; #pragma unroll
;         for (int db = 0; db < 2; ++db) {
;           const bf16x8 a = *(const bf16x8*)(vb + db * 32 * GP + kb2 * 32 + s2 * 16);
;           o[db] = MFMA(a, pf, o[db]);
;         }
;       }
;   }
.Lg_skipKA:
	global_load_dwordx4 v[160:163], v[130:131], off offset:-128
	global_load_dwordx4 v[164:167], v[180:181], off offset:-128
	v_exp_f32_e32 v48, v48
	v_exp_f32_e32 v49, v49
	v_exp_f32_e32 v50, v50
	v_add_f32_e32 v182, v48, v182
	v_exp_f32_e32 v51, v51
	v_add_f32_e32 v183, v49, v183
	v_exp_f32_e32 v52, v52
	v_add_f32_e32 v182, v50, v182
	s_waitcnt lgkmcnt(11)
	v_mfma_f32_32x32x16_bf16 v[80:95], v[96:99], v[136:139], 0
	v_exp_f32_e32 v53, v53
	v_add_f32_e32 v183, v51, v183
	v_exp_f32_e32 v54, v54
	v_add_f32_e32 v182, v52, v182
	v_exp_f32_e32 v55, v55
	s_waitcnt lgkmcnt(10)
	v_mfma_f32_32x32x16_bf16 v[64:79], v[100:103], v[136:139], 0
	v_add_f32_e32 v183, v53, v183
	v_cvt_pk_bf16_f32 v48, v48, v49
	v_add_f32_e32 v182, v54, v182
	v_cvt_pk_bf16_f32 v49, v50, v51
	v_add_f32_e32 v183, v55, v183
	s_waitcnt lgkmcnt(9)
	v_mfma_f32_32x32x16_bf16 v[80:95], v[104:107], v[140:143], v[80:95]
	v_cvt_pk_bf16_f32 v50, v52, v53
	v_cvt_pk_bf16_f32 v51, v54, v55
	v_exp_f32_e32 v56, v56
	v_exp_f32_e32 v57, v57
	v_exp_f32_e32 v58, v58
	s_waitcnt lgkmcnt(8)
	v_mfma_f32_32x32x16_bf16 v[64:79], v[108:111], v[140:143], v[64:79]
	v_add_f32_e32 v182, v56, v182
	v_exp_f32_e32 v59, v59
	v_add_f32_e32 v183, v57, v183
	v_exp_f32_e32 v60, v60
	v_add_f32_e32 v182, v58, v182
	s_waitcnt lgkmcnt(0)
	s_barrier
	ds_read_b128 v[96:99], v197 offset:18432
	ds_read_b128 v[100:103], v197 offset:23040
	ds_read_b128 v[104:107], v197 offset:18464
	ds_read_b128 v[108:111], v197 offset:23072
	v_mfma_f32_32x32x16_bf16 v[80:95], v[112:115], v[144:147], v[80:95]
	ds_read_b128 v[112:115], v197 offset:18496
	v_exp_f32_e32 v61, v61
	v_add_f32_e32 v183, v59, v183
	v_exp_f32_e32 v62, v62
	v_add_f32_e32 v182, v60, v182
	v_exp_f32_e32 v63, v63
	v_mfma_f32_32x32x16_bf16 v[64:79], v[116:119], v[144:147], v[64:79]
	ds_read_b128 v[116:119], v197 offset:23104
	v_add_f32_e32 v183, v61, v183
	v_cvt_pk_bf16_f32 v56, v56, v57
	v_add_f32_e32 v182, v62, v182
	v_cvt_pk_bf16_f32 v57, v58, v59
	v_add_f32_e32 v183, v63, v183
	v_mfma_f32_32x32x16_bf16 v[80:95], v[120:123], v[148:151], v[80:95]
	ds_read_b128 v[120:123], v197 offset:18528
	v_cvt_pk_bf16_f32 v58, v60, v61
	v_cvt_pk_bf16_f32 v59, v62, v63
	v_exp_f32_e32 v32, v32
	v_exp_f32_e32 v33, v33
	v_exp_f32_e32 v34, v34
	v_mfma_f32_32x32x16_bf16 v[64:79], v[124:127], v[148:151], v[64:79]
	ds_read_b128 v[124:127], v197 offset:23136
	v_add_f32_e32 v182, v32, v182
	v_exp_f32_e32 v35, v35
	v_add_f32_e32 v183, v33, v183
	v_exp_f32_e32 v36, v36
	v_add_f32_e32 v182, v34, v182
	v_mfma_f32_32x32x16_bf16 v[80:95], v[132:135], v[168:171], v[80:95]
	v_exp_f32_e32 v37, v37
	v_add_f32_e32 v183, v35, v183
	v_exp_f32_e32 v38, v38
	v_add_f32_e32 v182, v36, v182
	v_exp_f32_e32 v39, v39
	v_mfma_f32_32x32x16_bf16 v[64:79], v[132:135], v[168:171], v[64:79]
	v_add_f32_e32 v183, v37, v183
	v_cvt_pk_bf16_f32 v32, v32, v33
	v_add_f32_e32 v182, v38, v182
	v_cvt_pk_bf16_f32 v33, v34, v35
	v_add_f32_e32 v183, v39, v183
	s_waitcnt lgkmcnt(7)
	v_mfma_f32_32x32x16_bf16 v[16:31], v[96:99], v[48:51], v[16:31]
	ds_read_b128 v[96:99], v195
	v_cvt_pk_bf16_f32 v34, v36, v37
	v_cvt_pk_bf16_f32 v35, v38, v39
	v_exp_f32_e32 v40, v40
	v_exp_f32_e32 v41, v41
	v_exp_f32_e32 v42, v42
	s_waitcnt lgkmcnt(7)
	v_mfma_f32_32x32x16_bf16 v[0:15], v[100:103], v[48:51], v[0:15]
	ds_read_b128 v[100:103], v195 offset:4608
	v_add_f32_e32 v182, v40, v182
	v_exp_f32_e32 v43, v43
	v_add_f32_e32 v183, v41, v183
	v_exp_f32_e32 v44, v44
	v_add_f32_e32 v182, v42, v182
	s_waitcnt lgkmcnt(7)
	v_mfma_f32_32x32x16_bf16 v[16:31], v[104:107], v[56:59], v[16:31]
	ds_read_b128 v[104:107], v195 offset:32
	v_exp_f32_e32 v45, v45
	v_add_f32_e32 v183, v43, v183
	v_exp_f32_e32 v46, v46
	v_add_f32_e32 v182, v44, v182
	v_exp_f32_e32 v47, v47
	s_waitcnt lgkmcnt(7)
	v_mfma_f32_32x32x16_bf16 v[0:15], v[108:111], v[56:59], v[0:15]
	ds_read_b128 v[108:111], v195 offset:4640
	v_add_f32_e32 v183, v45, v183
	v_cvt_pk_bf16_f32 v40, v40, v41
	v_add_f32_e32 v182, v46, v182
	v_cvt_pk_bf16_f32 v41, v42, v43
	v_add_f32_e32 v183, v47, v183
	s_waitcnt lgkmcnt(7)
	v_mfma_f32_32x32x16_bf16 v[16:31], v[112:115], v[32:35], v[16:31]
	ds_read_b128 v[112:115], v195 offset:64
	v_cvt_pk_bf16_f32 v42, v44, v45
	v_cvt_pk_bf16_f32 v43, v46, v47
	v_max3_f32 v128, v80, v64, v81
	v_max3_f32 v172, v65, v82, v66
	v_max3_f32 v128, v83, v67, v128
	s_waitcnt lgkmcnt(7)
	v_mfma_f32_32x32x16_bf16 v[0:15], v[116:119], v[32:35], v[0:15]
	ds_read_b128 v[116:119], v195 offset:4672
	v_max3_f32 v172, v84, v68, v172
	v_max3_f32 v128, v85, v69, v128
	v_max3_f32 v172, v86, v70, v172
	v_max3_f32 v128, v87, v71, v128
	v_max3_f32 v172, v88, v72, v172
	s_waitcnt lgkmcnt(7)
	v_mfma_f32_32x32x16_bf16 v[16:31], v[120:123], v[40:43], v[16:31]
	ds_read_b128 v[120:123], v195 offset:96
	v_max3_f32 v128, v89, v73, v128
	v_max3_f32 v172, v90, v74, v172
	v_max3_f32 v128, v91, v75, v128
	v_max3_f32 v172, v92, v76, v172
	s_waitcnt lgkmcnt(7)
	v_mfma_f32_32x32x16_bf16 v[0:15], v[124:127], v[40:43], v[0:15]
	ds_read_b128 v[124:127], v195 offset:4704
	v_max3_f32 v128, v93, v77, v128
	v_max3_f32 v172, v94, v78, v172
	v_max3_f32 v128, v95, v79, v128
	v_max_f32_e32 v128, v128, v172
	s_waitcnt vmcnt(0)
	ds_write_b128 v248, v[152:155] offset:9216
	ds_write_b128 v249, v[156:159] offset:9216
	ds_write_b128 v194, v[160:163] offset:27648
	ds_write_b128 v196, v[164:167] offset:27648
	v_cmp_lt_f32_e32 vcc, s65, v128
	s_cbranch_vccnz .Lg_rareB

; #define MFMA(a, b, c) __builtin_amdgcn_mfma_f32_32x32x16_bf16((a), (b), (c), 0, 0, 0)
; DI unsigned pack2(float a, float b) { f32x2v f = {a, b}; bf16x2v v = __builtin_convertvector(f, bf16x2v); return __builtin_bit_cast(unsigned, v); }
; DI float xhalf(float v) { return __shfl_xor(v, 32); }
;   template <int PAR>
;   DI void step(int t, f32x16 (&cur)[2], f32x16 (&nxt)[2]) {
;     if (t + 1 < nt) sstore_k(PAR ^ 1);
;     if (t > 0) sstore_v(PAR);
;     __syncthreads();
;     if (t + 1 < nt) qk(PAR ^ 1, nxt);
;     float mx = fmaxf(cur[0][0], cur[1][0]);
; #pragma unroll
;     for (int i = 1; i < 16; ++i) mx = fmaxf(fmaxf(cur[0][i], cur[1][i]), mx);
;     if (__builtin_amdgcn_ballot_w64(mx > ATT_THR) != 0ull) {
;       asm volatile("" ::: "memory");
;       mx = fmaxf(mx, xhalf(mx));
;       const float want = mref + fmaxf(mx, 0.f);
;       const float mn = __uint_as_float(pack2(want, 0.f) << 16);
;       const float d = mn - mref;
;       const float alpha = __builtin_amdgcn_exp2f(-d);
;       mref = mn;
;       l *= alpha;
; #pragma unroll
;       for (int a = 0; a < 2; ++a)
; #pragma unroll
;         for (int i = 0; i < 16; ++i) { o[a][i] *= alpha; cur[a][i] -= d; nxt[a][i] -= d; }
;       u32x4 q4 = {h == 0 ? (pack2(-mn, 0.f) & 0xffffu) : 0u, 0u, 0u, 0u};
;       qm = __builtin_bit_cast(bf16x8, q4);
;     }
;     float psum = 0.f;
; #pragma unroll
;     for (int kb2 = 0; kb2 < 2; ++kb2)
; #pragma unroll
;       for (int i = 0; i < 16; ++i) { const float pv = __builtin_amdgcn_exp2f(cur[kb2][i]); cur[kb2][i] = pv; psum += pv; }
;     l += psum;
;     if (t + 2 < nt) gload_k(t + 2);
;     if (t + 1 < nt) gload_v(t + 1);
;     const u16* vb = sV + PAR * VBUF + r * GP + h * 8;
; #pragma unroll
;     for (int kb2 = 0; kb2 < 2; ++kb2)
; #pragma unroll
;       for (int s2 = 0; s2 < 2; ++s2) {
;         u32x4 pk = {pack2(cur[kb2][8 * s2], cur[kb2][8 * s2 + 1]), pack2(cur[kb2][8 * s2 + 2], cur[kb2][8 * s2 + 3]),
;                     pack2(cur[kb2][8 * s2 + 4], cur[kb2][8 * s2 + 5]), pack2(cur[kb2][8 * s2 + 6], cur[kb2][8 * s2 + 7])};
;         const bf16x8 pf = __builtin_bit_cast(bf16x8, pk);
; #pragma unroll
;         for (int db = 0; db < 2; ++db) {
;           const bf16x8 a = *(const bf16x8*)(vb + db * 32 * GP + kb2 * 32 + s2 * 16);
;           o[db] = MFMA(a, pf, o[db]);
;         }
;       }
;   }
.Lg_skipVB:
	v_exp_f32_e32 v80, v80
	v_exp_f32_e32 v81, v81
	v_exp_f32_e32 v82, v82
	v_add_f32_e32 v182, v80, v182
	v_exp_f32_e32 v83, v83
	v_add_f32_e32 v183, v81, v183
	v_exp_f32_e32 v84, v84
	v_add_f32_e32 v182, v82, v182
	s_waitcnt lgkmcnt(11)
	v_mfma_f32_32x32x16_bf16 v[48:63], v[96:99], v[136:139], 0
	v_exp_f32_e32 v85, v85
	v_add_f32_e32 v183, v83, v183
	v_exp_f32_e32 v86, v86
	v_add_f32_e32 v182, v84, v182
	v_exp_f32_e32 v87, v87
	s_waitcnt lgkmcnt(10)
	v_mfma_f32_32x32x16_bf16 v[32:47], v[100:103], v[136:139], 0
	v_add_f32_e32 v183, v85, v183
	v_cvt_pk_bf16_f32 v80, v80, v81
	v_add_f32_e32 v182, v86, v182
	v_cvt_pk_bf16_f32 v81, v82, v83
	v_add_f32_e32 v183, v87, v183
	s_waitcnt lgkmcnt(9)
	v_mfma_f32_32x32x16_bf16 v[48:63], v[104:107], v[140:143], v[48:63]
	v_cvt_pk_bf16_f32 v82, v84, v85
	v_cvt_pk_bf16_f32 v83, v86, v87
	v_exp_f32_e32 v88, v88
	v_exp_f32_e32 v89, v89
	v_exp_f32_e32 v90, v90
	s_waitcnt lgkmcnt(8)
	v_mfma_f32_32x32x16_bf16 v[32:47], v[108:111], v[140:143], v[32:47]
	v_add_f32_e32 v182, v88, v182
	v_exp_f32_e32 v91, v91
	v_add_f32_e32 v183, v89, v183
	v_exp_f32_e32 v92, v92
	v_add_f32_e32 v182, v90, v182
	s_waitcnt lgkmcnt(0)
	s_barrier
	ds_read_b128 v[96:99], v197 offset:27648
	ds_read_b128 v[100:103], v197 offset:32256
	ds_read_b128 v[104:107], v197 offset:27680
	ds_read_b128 v[108:111], v197 offset:32288
	v_mfma_f32_32x32x16_bf16 v[48:63], v[112:115], v[144:147], v[48:63]
	ds_read_b128 v[112:115], v197 offset:27712
	v_exp_f32_e32 v93, v93
	v_add_f32_e32 v183, v91, v183
	v_exp_f32_e32 v94, v94
	v_add_f32_e32 v182, v92, v182
	v_exp_f32_e32 v95, v95
	v_mfma_f32_32x32x16_bf16 v[32:47], v[116:119], v[144:147], v[32:47]
	ds_read_b128 v[116:119], v197 offset:32320
	v_add_f32_e32 v183, v93, v183
	v_cvt_pk_bf16_f32 v88, v88, v89
	v_add_f32_e32 v182, v94, v182
	v_cvt_pk_bf16_f32 v89, v90, v91
	v_add_f32_e32 v183, v95, v183
	v_mfma_f32_32x32x16_bf16 v[48:63], v[120:123], v[148:151], v[48:63]
	ds_read_b128 v[120:123], v197 offset:27744
	v_cvt_pk_bf16_f32 v90, v92, v93
	v_cvt_pk_bf16_f32 v91, v94, v95
	v_exp_f32_e32 v64, v64
	v_exp_f32_e32 v65, v65
	v_exp_f32_e32 v66, v66
	v_mfma_f32_32x32x16_bf16 v[32:47], v[124:127], v[148:151], v[32:47]
	ds_read_b128 v[124:127], v197 offset:32352
	v_add_f32_e32 v182, v64, v182
	v_exp_f32_e32 v67, v67
	v_add_f32_e32 v183, v65, v183
	v_exp_f32_e32 v68, v68
	v_add_f32_e32 v182, v66, v182
	v_mfma_f32_32x32x16_bf16 v[48:63], v[132:135], v[168:171], v[48:63]
	v_exp_f32_e32 v69, v69
	v_add_f32_e32 v183, v67, v183
	v_exp_f32_e32 v70, v70
	v_add_f32_e32 v182, v68, v182
	v_exp_f32_e32 v71, v71
	v_mfma_f32_32x32x16_bf16 v[32:47], v[132:135], v[168:171], v[32:47]
	v_add_f32_e32 v183, v69, v183
	v_cvt_pk_bf16_f32 v64, v64, v65
	v_add_f32_e32 v182, v70, v182
	v_cvt_pk_bf16_f32 v65, v66, v67
	v_add_f32_e32 v183, v71, v183
	s_waitcnt lgkmcnt(7)
	v_mfma_f32_32x32x16_bf16 v[16:31], v[96:99], v[80:83], v[16:31]
	ds_read_b128 v[96:99], v195 offset:9216
	v_cvt_pk_bf16_f32 v66, v68, v69
	v_cvt_pk_bf16_f32 v67, v70, v71
	v_exp_f32_e32 v72, v72
	v_exp_f32_e32 v73, v73
	v_exp_f32_e32 v74, v74
	s_waitcnt lgkmcnt(7)
	v_mfma_f32_32x32x16_bf16 v[0:15], v[100:103], v[80:83], v[0:15]
	ds_read_b128 v[100:103], v195 offset:13824
	v_add_f32_e32 v182, v72, v182
	v_exp_f32_e32 v75, v75
	v_add_f32_e32 v183, v73, v183
	v_exp_f32_e32 v76, v76
	v_add_f32_e32 v182, v74, v182
	s_waitcnt lgkmcnt(7)
	v_mfma_f32_32x32x16_bf16 v[16:31], v[104:107], v[88:91], v[16:31]
	ds_read_b128 v[104:107], v195 offset:9248
	v_exp_f32_e32 v77, v77
	v_add_f32_e32 v183, v75, v183
	v_exp_f32_e32 v78, v78
	v_add_f32_e32 v182, v76, v182
	v_exp_f32_e32 v79, v79
	s_waitcnt lgkmcnt(7)
	v_mfma_f32_32x32x16_bf16 v[0:15], v[108:111], v[88:91], v[0:15]
	ds_read_b128 v[108:111], v195 offset:13856
	v_add_f32_e32 v183, v77, v183
	v_cvt_pk_bf16_f32 v72, v72, v73
	v_add_f32_e32 v182, v78, v182
	v_cvt_pk_bf16_f32 v73, v74, v75
	v_add_f32_e32 v183, v79, v183
	s_waitcnt lgkmcnt(7)
	v_mfma_f32_32x32x16_bf16 v[16:31], v[112:115], v[64:67], v[16:31]
	ds_read_b128 v[112:115], v195 offset:9280
	v_cvt_pk_bf16_f32 v74, v76, v77
	v_cvt_pk_bf16_f32 v75, v78, v79
	v_max3_f32 v128, v48, v32, v49
	v_max3_f32 v172, v33, v50, v34
	v_max3_f32 v128, v51, v35, v128
	s_waitcnt lgkmcnt(7)
	v_mfma_f32_32x32x16_bf16 v[0:15], v[116:119], v[64:67], v[0:15]
	ds_read_b128 v[116:119], v195 offset:13888
	v_max3_f32 v172, v52, v36, v172
	v_max3_f32 v128, v53, v37, v128
	v_max3_f32 v172, v54, v38, v172
	v_max3_f32 v128, v55, v39, v128
	v_max3_f32 v172, v56, v40, v172
	s_waitcnt lgkmcnt(7)
	v_mfma_f32_32x32x16_bf16 v[16:31], v[120:123], v[72:75], v[16:31]
	ds_read_b128 v[120:123], v195 offset:9312
	v_max3_f32 v128, v57, v41, v128
	v_max3_f32 v172, v58, v42, v172
	v_max3_f32 v128, v59, v43, v128
	v_max3_f32 v172, v60, v44, v172
	s_waitcnt lgkmcnt(7)
	v_mfma_f32_32x32x16_bf16 v[0:15], v[124:127], v[72:75], v[0:15]
	ds_read_b128 v[124:127], v195 offset:13920
	v_max3_f32 v128, v61, v45, v128
	v_max3_f32 v172, v62, v46, v172
	v_max3_f32 v128, v63, v47, v128
	v_max_f32_e32 v128, v128, v172
	v_lshl_add_u64 v[130:131], v[130:131], 0, s[84:85]
	v_lshl_add_u64 v[180:181], v[180:181], 0, s[84:85]
	s_mov_b32 s0, s45
	s_add_i32 s45, s45, 2
	s_cmp_lt_u32 s0, s19
	s_cbranch_scc1 .LBB0_238
	s_branch .Lg_fold
; DI unsigned pack2(float a, float b) { f32x2v f = {a, b}; bf16x2v v = __builtin_convertvector(f, bf16x2v); return __builtin_bit_cast(unsigned, v); }
; DI float xhalf(float v) { return __shfl_xor(v, 32); }
;   template <int PAR>
;   DI void step(int t, f32x16 (&cur)[2], f32x16 (&nxt)[2]) {
;     ...
;     if (__builtin_amdgcn_ballot_w64(mx > ATT_THR) != 0ull) {
;       asm volatile("" ::: "memory");
;       mx = fmaxf(mx, xhalf(mx));
;       const float want = mref + fmaxf(mx, 0.f);
;       const float mn = __uint_as_float(pack2(want, 0.f) << 16);
;       const float d = mn - mref;
;       const float alpha = __builtin_amdgcn_exp2f(-d);
;       mref = mn;
;       l *= alpha;
; #pragma unroll
;       for (int a = 0; a < 2; ++a)
; #pragma unroll
;         for (int i = 0; i < 16; ++i) { o[a][i] *= alpha; cur[a][i] -= d; nxt[a][i] -= d; }
;       u32x4 q4 = {h == 0 ? (pack2(-mn, 0.f) & 0xffffu) : 0u, 0u, 0u, 0u};
;       qm = __builtin_bit_cast(bf16x8, q4);
;     }
.Lg_fold:
	s_waitcnt lgkmcnt(0)
	v_add_f32_e32 v173, v173, v182
	v_add_f32_e32 v173, v173, v183
	s_branch .LBB0_253
.Lgf_rareA:
	v_cmp_lt_i32_e64 s[0:1], v229, v228
	s_nop 1
	v_cndmask_b32_e64 v172, v227, v229, s[0:1]
	v_lshlrev_b32_e32 v172, 2, v172
	ds_bpermute_b32 v172, v172, v128
	s_waitcnt lgkmcnt(0)
	v_max3_f32 v128, v128, v172, 0
	v_add_f32_e32 v128, v178, v128
	v_cvt_pk_bf16_f32 v128, v128, 0
	v_lshlrev_b32_e32 v172, 16, v128
	v_sub_f32_e32 v128, v172, v178
	v_exp_f32_e64 v179, -v128
	v_sub_f32_e32 v48, v48, v128
	v_sub_f32_e32 v49, v49, v128
	v_sub_f32_e32 v50, v50, v128
	v_sub_f32_e32 v51, v51, v128
	v_sub_f32_e32 v52, v52, v128
	v_sub_f32_e32 v53, v53, v128
	v_sub_f32_e32 v54, v54, v128
	v_sub_f32_e32 v55, v55, v128
	v_sub_f32_e32 v56, v56, v128
	v_sub_f32_e32 v57, v57, v128
	v_sub_f32_e32 v58, v58, v128
	v_sub_f32_e32 v59, v59, v128
	v_sub_f32_e32 v60, v60, v128
	v_sub_f32_e32 v61, v61, v128
	v_sub_f32_e32 v62, v62, v128
	v_sub_f32_e32 v63, v63, v128
	v_sub_f32_e32 v32, v32, v128
	v_sub_f32_e32 v33, v33, v128
	v_sub_f32_e32 v34, v34, v128
	v_sub_f32_e32 v35, v35, v128
	v_sub_f32_e32 v36, v36, v128
	v_sub_f32_e32 v37, v37, v128
	v_sub_f32_e32 v38, v38, v128
	v_sub_f32_e32 v39, v39, v128
	v_sub_f32_e32 v40, v40, v128
	v_sub_f32_e32 v41, v41, v128
	v_sub_f32_e32 v42, v42, v128
	v_sub_f32_e32 v43, v43, v128
	v_sub_f32_e32 v44, v44, v128
	v_sub_f32_e32 v45, v45, v128
	v_sub_f32_e32 v46, v46, v128
	v_sub_f32_e32 v47, v47, v128
	v_xor_b32_e32 v128, 0x80000000, v172
	v_cvt_pk_bf16_f32 v128, v128, 0
	v_and_b32_e32 v128, 0xffff, v128
	v_mul_f32_e32 v173, v173, v179
	v_mul_f32_e32 v182, v182, v179
	v_mul_f32_e32 v183, v183, v179
	v_mul_f32_e32 v0, v0, v179
	v_mul_f32_e32 v1, v1, v179
	v_mul_f32_e32 v2, v2, v179
	v_mul_f32_e32 v3, v3, v179
	v_mul_f32_e32 v4, v4, v179
	v_mul_f32_e32 v5, v5, v179
	v_mul_f32_e32 v6, v6, v179
	v_mul_f32_e32 v7, v7, v179
	v_mul_f32_e32 v8, v8, v179
	v_mul_f32_e32 v9, v9, v179
	v_mul_f32_e32 v10, v10, v179
	v_mul_f32_e32 v11, v11, v179
	v_mul_f32_e32 v12, v12, v179
	v_mul_f32_e32 v13, v13, v179
	v_mul_f32_e32 v14, v14, v179
	v_mul_f32_e32 v15, v15, v179
	v_mul_f32_e32 v16, v16, v179
	v_mul_f32_e32 v17, v17, v179
	v_mul_f32_e32 v18, v18, v179
	v_mul_f32_e32 v19, v19, v179
	v_mul_f32_e32 v20, v20, v179
	v_mul_f32_e32 v21, v21, v179
	v_mul_f32_e32 v22, v22, v179
	v_mul_f32_e32 v23, v23, v179
	v_mul_f32_e32 v24, v24, v179
	v_mul_f32_e32 v25, v25, v179
	v_mul_f32_e32 v26, v26, v179
	v_mul_f32_e32 v27, v27, v179
	v_mul_f32_e32 v28, v28, v179
	v_mul_f32_e32 v29, v29, v179
	v_mul_f32_e32 v30, v30, v179
	v_mul_f32_e32 v31, v31, v179
	v_cndmask_b32_e64 v168, 0, v128, s[6:7]
	v_mov_b32_e32 v178, v172
	s_branch .Lg_rareA_ret
.Lgf_rareB:
	v_cmp_lt_i32_e64 s[0:1], v229, v228
	s_nop 1
	v_cndmask_b32_e64 v172, v227, v229, s[0:1]
	v_lshlrev_b32_e32 v172, 2, v172
	ds_bpermute_b32 v172, v172, v128
	s_waitcnt lgkmcnt(0)
	v_max3_f32 v128, v128, v172, 0
	v_add_f32_e32 v128, v178, v128
	v_cvt_pk_bf16_f32 v128, v128, 0
	v_lshlrev_b32_e32 v172, 16, v128
	v_sub_f32_e32 v128, v172, v178
	v_exp_f32_e64 v179, -v128
	v_sub_f32_e32 v80, v80, v128
	v_sub_f32_e32 v81, v81, v128
	v_sub_f32_e32 v82, v82, v128
	v_sub_f32_e32 v83, v83, v128
	v_sub_f32_e32 v84, v84, v128
	v_sub_f32_e32 v85, v85, v128
	v_sub_f32_e32 v86, v86, v128
	v_sub_f32_e32 v87, v87, v128
	v_sub_f32_e32 v88, v88, v128
	v_sub_f32_e32 v89, v89, v128
	v_sub_f32_e32 v90, v90, v128
	v_sub_f32_e32 v91, v91, v128
	v_sub_f32_e32 v92, v92, v128
	v_sub_f32_e32 v93, v93, v128
	v_sub_f32_e32 v94, v94, v128
	v_sub_f32_e32 v95, v95, v128
	v_sub_f32_e32 v64, v64, v128
	v_sub_f32_e32 v65, v65, v128
	v_sub_f32_e32 v66, v66, v128
	v_sub_f32_e32 v67, v67, v128
	v_sub_f32_e32 v68, v68, v128
	v_sub_f32_e32 v69, v69, v128
	v_sub_f32_e32 v70, v70, v128
	v_sub_f32_e32 v71, v71, v128
	v_sub_f32_e32 v72, v72, v128
	v_sub_f32_e32 v73, v73, v128
	v_sub_f32_e32 v74, v74, v128
	v_sub_f32_e32 v75, v75, v128
	v_sub_f32_e32 v76, v76, v128
	v_sub_f32_e32 v77, v77, v128
	v_sub_f32_e32 v78, v78, v128
	v_sub_f32_e32 v79, v79, v128
	v_xor_b32_e32 v128, 0x80000000, v172
	v_cvt_pk_bf16_f32 v128, v128, 0
	v_and_b32_e32 v128, 0xffff, v128
	v_mul_f32_e32 v173, v173, v179
	v_mul_f32_e32 v182, v182, v179
	v_mul_f32_e32 v183, v183, v179
	v_mul_f32_e32 v0, v0, v179
	v_mul_f32_e32 v1, v1, v179
	v_mul_f32_e32 v2, v2, v179
	v_mul_f32_e32 v3, v3, v179
	v_mul_f32_e32 v4, v4, v179
	v_mul_f32_e32 v5, v5, v179
	v_mul_f32_e32 v6, v6, v179
	v_mul_f32_e32 v7, v7, v179
	v_mul_f32_e32 v8, v8, v179
	v_mul_f32_e32 v9, v9, v179
	v_mul_f32_e32 v10, v10, v179
	v_mul_f32_e32 v11, v11, v179
	v_mul_f32_e32 v12, v12, v179
	v_mul_f32_e32 v13, v13, v179
	v_mul_f32_e32 v14, v14, v179
	v_mul_f32_e32 v15, v15, v179
	v_mul_f32_e32 v16, v16, v179
	v_mul_f32_e32 v17, v17, v179
	v_mul_f32_e32 v18, v18, v179
	v_mul_f32_e32 v19, v19, v179
	v_mul_f32_e32 v20, v20, v179
	v_mul_f32_e32 v21, v21, v179
	v_mul_f32_e32 v22, v22, v179
	v_mul_f32_e32 v23, v23, v179
	v_mul_f32_e32 v24, v24, v179
	v_mul_f32_e32 v25, v25, v179
	v_mul_f32_e32 v26, v26, v179
	v_mul_f32_e32 v27, v27, v179
	v_mul_f32_e32 v28, v28, v179
	v_mul_f32_e32 v29, v29, v179
	v_mul_f32_e32 v30, v30, v179
	v_mul_f32_e32 v31, v31, v179
	v_cndmask_b32_e64 v168, 0, v128, s[6:7]
	v_mov_b32_e32 v178, v172
	s_branch .Lg_rareB_ret

;   DI void gload_k(int t) {
;     const int row0 = rowk0 + t * 64;
;     const u16* kt = Kb + (size_t)row0 * kpitch;
;     const u16* pt = KPEb + (size_t)row0 * 32;
; #pragma unroll
;     for (int q = 0; q < NKL; ++q) {
;       const int c = tid + 256 * q, cc = c % KCH;
;       rk[q] = ldg16(((DQK == 96 && cc >= 8) ? pt : kt) + koff[q]);
;     }
;   }
;   DI void gload_v(int t) {
;     const u16* vt = Vt + (rowk0 + t * 64);
; #pragma unroll
;     for (int q = 0; q < 2; ++q) rv[q] = ldg16(vt + voff[q]);
;   }
;   DI void sstore_k(int buf) {
; #pragma unroll
;     for (int q = 0; q < NKL; ++q) {
;       const int c = tid + 256 * q, row = c / KCH, cc = c % KCH;
;       *(u32x4*)(sK + buf * KBUF + row * KP + cc * 8) = rk[q];
;     }
;   }
;   DI void sstore_v(int buf) {
; #pragma unroll
;     for (int q = 0; q < 2; ++q) {
;       const int c = tid + 256 * q, dv = c >> 3, kc = c & 7;
;       *(u32x4*)(sV + buf * VBUF + dv * GP + kc * 8) = rv[q];
;     }
;   }
;   DI void qk(int buf, f32x16 (&s)[2]) {
;     const u16* kb = sK + buf * KBUF + sr * KP + h * 8;
; #pragma unroll
;     for (int kb2 = 0; kb2 < 2; ++kb2)
; #pragma unroll
;       for (int i = 0; i < 16; ++i) s[kb2][i] = 0.f;
; #pragma unroll
;     for (int ks = 0; ks < NKS; ++ks)
; #pragma unroll
;       for (int kb2 = 0; kb2 < 2; ++kb2) {
;         const bf16x8 a = *(const bf16x8*)(kb + kb2 * 32 * KP + ks * 16);
;         s[kb2] = MFMA(a, qf[ks], s[kb2]);
;       }
;     s[0] = MFMA(kone, qm, s[0]);
;     s[1] = MFMA(kone, qm, s[1]);
;   }
;   template <int PAR>
;   DI void step(int t, f32x16 (&cur)[2], f32x16 (&nxt)[2]) {
; template <int DQK>
; DI void attn_item(const u16* __restrict__ Qb, int qpitch, const u16* __restrict__ Kb, int kpitch, const u16* __restrict__ KPEb,
;                   const u16* __restrict__ Vt, float* __restrict__ ssq, int rowq0, int rowk0, int nt, char* smem, int tid, bool dry) {
;     ...
;   c.gload_k(0); c.gload_v(0);
;   __syncthreads();
;   c.sstore_k(0); c.sstore_v(0);
;   if (nt > 1) c.gload_k(1);
;   __syncthreads();
;   c.qk(0, sa);
; #pragma unroll
;   for (int i = 0; i < 16; ++i) {
;     sa[0][i] = -1e30f;
;     if (swap23(crow(i, h)) < 16) sa[1][i] = -1e30f;
;   }
;   int t = 0;
;   for (; t + 1 < nt; t += 2) {
;     c.template step<0>(t, sa, sb);
;     c.template step<1>(t + 1, sb, sa);
;   }
;   if (t < nt) c.template step<0>(t, sa, sb);
.Lm_entry:
	v_mov_b32_e32 v181, 0
	v_mov_b32_e32 v182, 0
	v_mov_b32_e32 v183, 0
	v_mov_b32_e32 v238, 0
	v_mov_b32_e32 v239, 0
	s_waitcnt vmcnt(2)
	ds_write_b128 v250, v[160:163] offset:13312
	ds_write_b128 v251, v[164:167] offset:13312
	ds_write_b128 v252, v[168:171] offset:13312
	s_sub_i32 s0, s44, 64
	s_ashr_i32 s1, s0, 31
	s_lshl_b64 s[20:21], s[0:1], 10
	s_lshl_b64 s[0:1], s[0:1], 6
	s_add_u32 s20, s26, s20
	s_addc_u32 s21, s27, s21
	s_add_u32 s44, s81, s0
	s_addc_u32 s45, s64, s1
	v_mov_b32_e32 v160, s21
	v_mov_b32_e32 v161, s45
	v_mov_b32_e32 v162, s20
	v_mov_b32_e32 v163, s44
	v_cndmask_b32_e64 v169, v160, v161, s[12:13]
	v_cndmask_b32_e64 v168, v162, v163, s[12:13]
	v_lshl_add_u64 v[168:169], v[204:205], 1, v[168:169]
	v_cndmask_b32_e64 v165, v160, v161, s[10:11]
	v_cndmask_b32_e64 v164, v162, v163, s[10:11]
	v_lshl_add_u64 v[164:165], v[202:203], 1, v[164:165]
	v_cndmask_b32_e64 v167, v160, v161, s[8:9]
	v_cndmask_b32_e64 v166, v162, v163, s[8:9]
	v_lshl_add_u64 v[166:167], v[200:201], 1, v[166:167]
	global_load_dwordx4 v[168:171], v[168:169], off
	global_load_dwordx4 v[160:163], v[166:167], off
	global_load_dwordx4 v[164:167], v[164:165], off
	s_add_u32 s20, s20, 0x10000
	s_addc_u32 s21, s21, 0
	s_add_u32 s44, s44, 0x1000
	s_addc_u32 s45, s45, 0
.Lm_entryK:
	s_waitcnt lgkmcnt(0)
	s_barrier
	ds_read_b128 v[112:115], v236 offset:13376
	ds_read_b128 v[116:119], v236 offset:20032
	ds_read_b128 v[120:123], v236 offset:13408
	ds_read_b128 v[124:127], v236 offset:20064
	ds_read_b128 v[96:99], v236 offset:13312
	ds_read_b128 v[100:103], v236 offset:19968
	ds_read_b128 v[104:107], v236 offset:13344
	ds_read_b128 v[108:111], v236 offset:20000
	v_max3_f32 v240, v48, v32, v49
	v_max3_f32 v241, v33, v50, v34
	v_max3_f32 v240, v51, v35, v240
	v_max3_f32 v241, v52, v36, v241
	v_max3_f32 v240, v53, v37, v240
	v_max3_f32 v241, v54, v38, v241
	v_max3_f32 v240, v55, v39, v240
	v_max3_f32 v241, v56, v40, v241
	v_max3_f32 v240, v57, v41, v240
	v_max3_f32 v241, v58, v42, v241
	v_max3_f32 v240, v59, v43, v240
	v_max3_f32 v241, v60, v44, v241
	v_max3_f32 v240, v61, v45, v240
	v_max3_f32 v241, v62, v46, v241
	v_max3_f32 v240, v63, v47, v240
	v_max_f32_e32 v240, v240, v241
	v_and_b32_e32 v181, 0x7fff, v180
	v_cmp_ne_u32_e32 vcc, 0, v181
	v_mov_b32_e32 v181, 0
	s_cbranch_vccnz .LBB0_268
.Lmf_top:
	s_waitcnt vmcnt(0)
	ds_write_b128 v250, v[160:163]
	ds_write_b128 v251, v[164:167]
	ds_write_b128 v252, v[168:171]
	ds_write_b128 v194, v[172:175] offset:26624
	ds_write_b128 v196, v[176:179] offset:26624
	v_cmp_lt_f32_e32 vcc, s65, v240
	s_cbranch_vccnz .Lmf_rareA
.Lmf_rareA_ret:
	s_add_i32 s0, s31, -1
	s_cmp_ge_u32 s0, s19
	s_cselect_b64 s[14:15], -1, 0
	s_cmp_ge_u32 s31, s19
	s_cbranch_scc1 .Lmf_skipKA
	v_mov_b32_e32 v160, s21
	v_mov_b32_e32 v161, s45
	v_mov_b32_e32 v162, s20
	v_mov_b32_e32 v163, s44
	v_cndmask_b32_e64 v169, v160, v161, s[12:13]
	v_cndmask_b32_e64 v168, v162, v163, s[12:13]
	v_lshl_add_u64 v[168:169], v[204:205], 1, v[168:169]
	v_cndmask_b32_e64 v165, v160, v161, s[10:11]
	v_cndmask_b32_e64 v164, v162, v163, s[10:11]
	v_lshl_add_u64 v[164:165], v[202:203], 1, v[164:165]
	v_cndmask_b32_e64 v167, v160, v161, s[8:9]
	v_cndmask_b32_e64 v166, v162, v163, s[8:9]
	v_lshl_add_u64 v[166:167], v[200:201], 1, v[166:167]
	global_load_dwordx4 v[168:171], v[168:169], off
	global_load_dwordx4 v[160:163], v[166:167], off
	global_load_dwordx4 v[164:167], v[164:165], off
	s_add_u32 s20, s20, 0x10000
	s_addc_u32 s21, s21, 0
	s_add_u32 s44, s44, 0x1000
	s_addc_u32 s45, s45, 0
; #define MFMA(a, b, c) __builtin_amdgcn_mfma_f32_32x32x16_bf16((a), (b), (c), 0, 0, 0)
; DI unsigned pack2(float a, float b) { f32x2v f = {a, b}; bf16x2v v = __builtin_convertvector(f, bf16x2v); return __builtin_bit_cast(unsigned, v); }
; DI float xhalf(float v) { return __shfl_xor(v, 32); }
;   template <int PAR>
;   DI void step(int t, f32x16 (&cur)[2], f32x16 (&nxt)[2]) {
;     if (t + 1 < nt) sstore_k(PAR ^ 1);
;     if (t > 0) sstore_v(PAR);
;     __syncthreads();
;     if (t + 1 < nt) qk(PAR ^ 1, nxt);
;     float mx = fmaxf(cur[0][0], cur[1][0]);
; #pragma unroll
;     for (int i = 1; i < 16; ++i) mx = fmaxf(fmaxf(cur[0][i], cur[1][i]), mx);
;     if (__builtin_amdgcn_ballot_w64(mx > ATT_THR) != 0ull) {
;       asm volatile("" ::: "memory");
;       mx = fmaxf(mx, xhalf(mx));
;       const float want = mref + fmaxf(mx, 0.f);
;       const float mn = __uint_as_float(pack2(want, 0.f) << 16);
;       const float d = mn - mref;
;       const float alpha = __builtin_amdgcn_exp2f(-d);
;       mref = mn;
;       l *= alpha;
; #pragma unroll
;       for (int a = 0; a < 2; ++a)
; #pragma unroll
;         for (int i = 0; i < 16; ++i) { o[a][i] *= alpha; cur[a][i] -= d; nxt[a][i] -= d; }
;       u32x4 q4 = {h == 0 ? (pack2(-mn, 0.f) & 0xffffu) : 0u, 0u, 0u, 0u};
;       qm = __builtin_bit_cast(bf16x8, q4);
;     }
;     float psum = 0.f;
; #pragma unroll
;     for (int kb2 = 0; kb2 < 2; ++kb2)
; #pragma unroll
;       for (int i = 0; i < 16; ++i) { const float pv = __builtin_amdgcn_exp2f(cur[kb2][i]); cur[kb2][i] = pv; psum += pv; }
;     l += psum;
;     if (t + 2 < nt) gload_k(t + 2);
;     if (t + 1 < nt) gload_v(t + 1);
;     const u16* vb = sV + PAR * VBUF + r * GP + h * 8;
; #pragma unroll
;     for (int kb2 = 0; kb2 < 2; ++kb2)
; #pragma unroll
;       for (int s2 = 0; s2 < 2; ++s2) {
;         u32x4 pk = {pack2(cur[kb2][8 * s2], cur[kb2][8 * s2 + 1]), pack2(cur[kb2][8 * s2 + 2], cur[kb2][8 * s2 + 3]),
;                     pack2(cur[kb2][8 * s2 + 4], cur[kb2][8 * s2 + 5]), pack2(cur[kb2][8 * s2 + 6], cur[kb2][8 * s2 + 7])};
;         const bf16x8 pf = __builtin_bit_cast(bf16x8, pk);
; #pragma unroll
;         for (int db = 0; db < 2; ++db) {
;           const bf16x8 a = *(const bf16x8*)(vb + db * 32 * GP + kb2 * 32 + s2 * 16);
;           o[db] = MFMA(a, pf, o[db]);
;         }
;       }
;   }
.Lmf_skipKA:
	global_load_dwordx4 v[172:175], v[130:131], off offset:-128
	global_load_dwordx4 v[176:179], v[220:221], off offset:-128
	v_exp_f32_e32 v48, v48
	v_exp_f32_e32 v49, v49
	v_exp_f32_e32 v50, v50
	v_add_f32_e32 v238, v48, v238
	v_exp_f32_e32 v51, v51
	v_add_f32_e32 v239, v49, v239
	v_exp_f32_e32 v52, v52
	v_add_f32_e32 v238, v50, v238
	s_waitcnt lgkmcnt(8)
	v_mfma_f32_32x32x16_bf16 v[80:95], v[96:99], v[136:139], 0
	ds_read_b128 v[96:99], v236 offset:13440
	v_exp_f32_e32 v53, v53
	v_add_f32_e32 v239, v51, v239
	v_exp_f32_e32 v54, v54
	v_add_f32_e32 v238, v52, v238
	v_exp_f32_e32 v55, v55
	s_waitcnt lgkmcnt(8)
	v_mfma_f32_32x32x16_bf16 v[64:79], v[100:103], v[136:139], 0
	ds_read_b128 v[100:103], v236 offset:20096
	v_add_f32_e32 v239, v53, v239
	v_cvt_pk_bf16_f32 v48, v48, v49
	v_add_f32_e32 v238, v54, v238
	v_cvt_pk_bf16_f32 v49, v50, v51
	v_add_f32_e32 v239, v55, v239
	s_waitcnt lgkmcnt(8)
	v_mfma_f32_32x32x16_bf16 v[80:95], v[104:107], v[140:143], v[80:95]
	ds_read_b128 v[104:107], v236 offset:13472
	v_cvt_pk_bf16_f32 v50, v52, v53
	v_cvt_pk_bf16_f32 v51, v54, v55
	v_exp_f32_e32 v56, v56
	v_exp_f32_e32 v57, v57
	v_exp_f32_e32 v58, v58
	s_waitcnt lgkmcnt(8)
	v_mfma_f32_32x32x16_bf16 v[64:79], v[108:111], v[140:143], v[64:79]
	ds_read_b128 v[108:111], v236 offset:20128
	v_add_f32_e32 v238, v56, v238
	v_exp_f32_e32 v59, v59
	v_add_f32_e32 v239, v57, v239
	v_exp_f32_e32 v60, v60
	v_add_f32_e32 v238, v58, v238
	s_waitcnt lgkmcnt(0)
	s_barrier
	v_mfma_f32_32x32x16_bf16 v[80:95], v[112:115], v[144:147], v[80:95]
	ds_read_b128 v[112:115], v197 offset:26624
	v_exp_f32_e32 v61, v61
	v_add_f32_e32 v239, v59, v239
	v_exp_f32_e32 v62, v62
	v_add_f32_e32 v238, v60, v238
	v_exp_f32_e32 v63, v63
	v_mfma_f32_32x32x16_bf16 v[64:79], v[116:119], v[144:147], v[64:79]
	ds_read_b128 v[116:119], v197 offset:31232
	v_add_f32_e32 v239, v61, v239
	v_cvt_pk_bf16_f32 v56, v56, v57
	v_add_f32_e32 v238, v62, v238
	v_cvt_pk_bf16_f32 v57, v58, v59
	v_add_f32_e32 v239, v63, v239
	v_mfma_f32_32x32x16_bf16 v[80:95], v[120:123], v[148:151], v[80:95]
	ds_read_b128 v[120:123], v197 offset:26656
	v_cvt_pk_bf16_f32 v58, v60, v61
	v_cvt_pk_bf16_f32 v59, v62, v63
	v_exp_f32_e32 v32, v32
	v_exp_f32_e32 v33, v33
	v_exp_f32_e32 v34, v34
	v_mfma_f32_32x32x16_bf16 v[64:79], v[124:127], v[148:151], v[64:79]
	ds_read_b128 v[124:127], v197 offset:31264
	v_add_f32_e32 v238, v32, v238
	v_exp_f32_e32 v35, v35
	v_add_f32_e32 v239, v33, v239
	v_exp_f32_e32 v36, v36
	v_add_f32_e32 v238, v34, v238
	v_mfma_f32_32x32x16_bf16 v[80:95], v[96:99], v[152:155], v[80:95]
	ds_read_b128 v[96:99], v197 offset:26688
	v_exp_f32_e32 v37, v37
	v_add_f32_e32 v239, v35, v239
	v_exp_f32_e32 v38, v38
	v_add_f32_e32 v238, v36, v238
	v_mfma_f32_32x32x16_bf16 v[64:79], v[100:103], v[152:155], v[64:79]
	ds_read_b128 v[100:103], v197 offset:31296
	v_exp_f32_e32 v39, v39
	v_add_f32_e32 v239, v37, v239
	v_cvt_pk_bf16_f32 v32, v32, v33
	v_add_f32_e32 v238, v38, v238
	v_mfma_f32_32x32x16_bf16 v[80:95], v[104:107], v[156:159], v[80:95]
	ds_read_b128 v[104:107], v197 offset:26720
	v_cvt_pk_bf16_f32 v33, v34, v35
	v_add_f32_e32 v239, v39, v239
	v_cvt_pk_bf16_f32 v34, v36, v37
	v_cvt_pk_bf16_f32 v35, v38, v39
	v_mfma_f32_32x32x16_bf16 v[64:79], v[108:111], v[156:159], v[64:79]
	ds_read_b128 v[108:111], v197 offset:31328
	v_exp_f32_e32 v40, v40
	v_exp_f32_e32 v41, v41
	v_exp_f32_e32 v42, v42
	v_add_f32_e32 v238, v40, v238
	s_waitcnt lgkmcnt(7)
	v_mfma_f32_32x32x16_bf16 v[16:31], v[112:115], v[48:51], v[16:31]
	ds_read_b128 v[112:115], v236 offset:64
	v_exp_f32_e32 v43, v43
	v_add_f32_e32 v239, v41, v239
	v_exp_f32_e32 v44, v44
	v_add_f32_e32 v238, v42, v238
	s_waitcnt lgkmcnt(7)
	v_mfma_f32_32x32x16_bf16 v[0:15], v[116:119], v[48:51], v[0:15]
	ds_read_b128 v[116:119], v236 offset:6720
	v_exp_f32_e32 v45, v45
	v_add_f32_e32 v239, v43, v239
	v_exp_f32_e32 v46, v46
	v_add_f32_e32 v238, v44, v238
	s_waitcnt lgkmcnt(7)
	v_mfma_f32_32x32x16_bf16 v[16:31], v[120:123], v[56:59], v[16:31]
	ds_read_b128 v[120:123], v236 offset:96
	v_exp_f32_e32 v47, v47
	v_add_f32_e32 v239, v45, v239
	v_cvt_pk_bf16_f32 v40, v40, v41
	v_add_f32_e32 v238, v46, v238
	s_waitcnt lgkmcnt(7)
	v_mfma_f32_32x32x16_bf16 v[0:15], v[124:127], v[56:59], v[0:15]
	ds_read_b128 v[124:127], v236 offset:6752
	v_cvt_pk_bf16_f32 v41, v42, v43
	v_add_f32_e32 v239, v47, v239
	v_cvt_pk_bf16_f32 v42, v44, v45
	v_cvt_pk_bf16_f32 v43, v46, v47
	s_waitcnt lgkmcnt(7)
	v_mfma_f32_32x32x16_bf16 v[16:31], v[96:99], v[32:35], v[16:31]
	ds_read_b128 v[96:99], v236
	v_max3_f32 v240, v80, v64, v81
	v_max3_f32 v241, v65, v82, v66
	v_max3_f32 v240, v83, v67, v240
	v_max3_f32 v241, v84, v68, v241
	s_waitcnt lgkmcnt(7)
	v_mfma_f32_32x32x16_bf16 v[0:15], v[100:103], v[32:35], v[0:15]
	ds_read_b128 v[100:103], v236 offset:6656
	v_max3_f32 v240, v85, v69, v240
	v_max3_f32 v241, v86, v70, v241
	v_max3_f32 v240, v87, v71, v240
	v_max3_f32 v241, v88, v72, v241
	s_waitcnt lgkmcnt(7)
	v_mfma_f32_32x32x16_bf16 v[16:31], v[104:107], v[40:43], v[16:31]
	ds_read_b128 v[104:107], v236 offset:32
	v_max3_f32 v240, v89, v73, v240
	v_max3_f32 v241, v90, v74, v241
	v_max3_f32 v240, v91, v75, v240
	v_max3_f32 v241, v92, v76, v241
	s_waitcnt lgkmcnt(7)
	v_mfma_f32_32x32x16_bf16 v[0:15], v[108:111], v[40:43], v[0:15]
	ds_read_b128 v[108:111], v236 offset:6688
	v_max3_f32 v240, v93, v77, v240
	v_max3_f32 v241, v94, v78, v241
	v_max3_f32 v240, v95, v79, v240
	v_max_f32_e32 v240, v240, v241
	s_waitcnt vmcnt(0)
	ds_write_b128 v250, v[160:163] offset:13312
	ds_write_b128 v251, v[164:167] offset:13312
	ds_write_b128 v252, v[168:171] offset:13312
	ds_write_b128 v194, v[172:175] offset:35840
	ds_write_b128 v196, v[176:179] offset:35840
	v_cmp_lt_f32_e32 vcc, s65, v240
	s_cbranch_vccnz .Lmf_rareB
.Lmf_rareB_ret:
	s_add_i32 s0, s31, 1
	s_cmp_ge_u32 s0, s19
	s_cbranch_scc1 .Lmf_skipKB
	v_mov_b32_e32 v160, s21
	v_mov_b32_e32 v161, s45
	v_mov_b32_e32 v162, s20
	v_mov_b32_e32 v163, s44
	v_cndmask_b32_e64 v169, v160, v161, s[12:13]
	v_cndmask_b32_e64 v168, v162, v163, s[12:13]
	v_lshl_add_u64 v[168:169], v[204:205], 1, v[168:169]
	v_cndmask_b32_e64 v165, v160, v161, s[10:11]
	v_cndmask_b32_e64 v164, v162, v163, s[10:11]
	v_lshl_add_u64 v[164:165], v[202:203], 1, v[164:165]
	v_cndmask_b32_e64 v167, v160, v161, s[8:9]
	v_cndmask_b32_e64 v166, v162, v163, s[8:9]
	v_lshl_add_u64 v[166:167], v[200:201], 1, v[166:167]
	global_load_dwordx4 v[168:171], v[168:169], off
	global_load_dwordx4 v[160:163], v[166:167], off
	global_load_dwordx4 v[164:167], v[164:165], off
	s_add_u32 s20, s20, 0x10000
	s_addc_u32 s21, s21, 0
	s_add_u32 s44, s44, 0x1000
	s_addc_u32 s45, s45, 0

; #define MFMA(a, b, c) __builtin_amdgcn_mfma_f32_32x32x16_bf16((a), (b), (c), 0, 0, 0)
; DI unsigned pack2(float a, float b) { f32x2v f = {a, b}; bf16x2v v = __builtin_convertvector(f, bf16x2v); return __builtin_bit_cast(unsigned, v); }
;   DI void qk(int buf, f32x16 (&s)[2]) {
;     const u16* kb = sK + buf * KBUF + sr * KP + h * 8;
; #pragma unroll
;     for (int kb2 = 0; kb2 < 2; ++kb2)
; #pragma unroll
;       for (int i = 0; i < 16; ++i) s[kb2][i] = 0.f;
; #pragma unroll
;     for (int ks = 0; ks < NKS; ++ks)
; #pragma unroll
;       for (int kb2 = 0; kb2 < 2; ++kb2) {
;         const bf16x8 a = *(const bf16x8*)(kb + kb2 * 32 * KP + ks * 16);
;         s[kb2] = MFMA(a, qf[ks], s[kb2]);
;       }
;     s[0] = MFMA(kone, qm, s[0]);
;     s[1] = MFMA(kone, qm, s[1]);
;   template <int PAR>
;   DI void step(int t, f32x16 (&cur)[2], f32x16 (&nxt)[2]) {
;     ...
;     float psum = 0.f;
; #pragma unroll
;     for (int kb2 = 0; kb2 < 2; ++kb2)
; #pragma unroll
;       for (int i = 0; i < 16; ++i) { const float pv = __builtin_amdgcn_exp2f(cur[kb2][i]); cur[kb2][i] = pv; psum += pv; }
;     l += psum;
;     if (t + 2 < nt) gload_k(t + 2);
;     if (t + 1 < nt) gload_v(t + 1);
;     const u16* vb = sV + PAR * VBUF + r * GP + h * 8;
; #pragma unroll
;     for (int kb2 = 0; kb2 < 2; ++kb2)
; #pragma unroll
;       for (int s2 = 0; s2 < 2; ++s2) {
;         u32x4 pk = {pack2(cur[kb2][8 * s2], cur[kb2][8 * s2 + 1]), pack2(cur[kb2][8 * s2 + 2], cur[kb2][8 * s2 + 3]),
;                     pack2(cur[kb2][8 * s2 + 4], cur[kb2][8 * s2 + 5]), pack2(cur[kb2][8 * s2 + 6], cur[kb2][8 * s2 + 7])};
;         const bf16x8 pf = __builtin_bit_cast(bf16x8, pk);
; #pragma unroll
;         for (int db = 0; db < 2; ++db) {
;           const bf16x8 a = *(const bf16x8*)(vb + db * 32 * GP + kb2 * 32 + s2 * 16);
;           o[db] = MFMA(a, pf, o[db]);
;         }
;       }
.Lmf_skipVB:
	v_exp_f32_e32 v80, v80
	v_exp_f32_e32 v81, v81
	v_exp_f32_e32 v82, v82
	v_add_f32_e32 v238, v80, v238
	v_exp_f32_e32 v83, v83
	v_add_f32_e32 v239, v81, v239
	v_exp_f32_e32 v84, v84
	v_add_f32_e32 v238, v82, v238
	s_waitcnt lgkmcnt(8)
	v_mfma_f32_32x32x16_bf16 v[48:63], v[96:99], v[136:139], 0
	ds_read_b128 v[96:99], v236 offset:128
	v_exp_f32_e32 v85, v85
	v_add_f32_e32 v239, v83, v239
	v_exp_f32_e32 v86, v86
	v_add_f32_e32 v238, v84, v238
	v_exp_f32_e32 v87, v87
	s_waitcnt lgkmcnt(8)
	v_mfma_f32_32x32x16_bf16 v[32:47], v[100:103], v[136:139], 0
	ds_read_b128 v[100:103], v236 offset:6784
	v_add_f32_e32 v239, v85, v239
	v_cvt_pk_bf16_f32 v80, v80, v81
	v_add_f32_e32 v238, v86, v238
	v_cvt_pk_bf16_f32 v81, v82, v83
	v_add_f32_e32 v239, v87, v239
	s_waitcnt lgkmcnt(8)
	v_mfma_f32_32x32x16_bf16 v[48:63], v[104:107], v[140:143], v[48:63]
	ds_read_b128 v[104:107], v236 offset:160
	v_cvt_pk_bf16_f32 v82, v84, v85
	v_cvt_pk_bf16_f32 v83, v86, v87
	v_exp_f32_e32 v88, v88
	v_exp_f32_e32 v89, v89
	v_exp_f32_e32 v90, v90
	s_waitcnt lgkmcnt(8)
	v_mfma_f32_32x32x16_bf16 v[32:47], v[108:111], v[140:143], v[32:47]
	ds_read_b128 v[108:111], v236 offset:6816
	v_add_f32_e32 v238, v88, v238
	v_exp_f32_e32 v91, v91
	v_add_f32_e32 v239, v89, v239
	v_exp_f32_e32 v92, v92
	v_add_f32_e32 v238, v90, v238
	s_waitcnt lgkmcnt(0)
	s_barrier
	v_mfma_f32_32x32x16_bf16 v[48:63], v[112:115], v[144:147], v[48:63]
	ds_read_b128 v[112:115], v197 offset:35840
	v_exp_f32_e32 v93, v93
	v_add_f32_e32 v239, v91, v239
	v_exp_f32_e32 v94, v94
	v_add_f32_e32 v238, v92, v238
	v_exp_f32_e32 v95, v95
	v_mfma_f32_32x32x16_bf16 v[32:47], v[116:119], v[144:147], v[32:47]
	ds_read_b128 v[116:119], v197 offset:40448
	v_add_f32_e32 v239, v93, v239
	v_cvt_pk_bf16_f32 v88, v88, v89
	v_add_f32_e32 v238, v94, v238
	v_cvt_pk_bf16_f32 v89, v90, v91
	v_add_f32_e32 v239, v95, v239
	v_mfma_f32_32x32x16_bf16 v[48:63], v[120:123], v[148:151], v[48:63]
	ds_read_b128 v[120:123], v197 offset:35872
	v_cvt_pk_bf16_f32 v90, v92, v93
	v_cvt_pk_bf16_f32 v91, v94, v95
	v_exp_f32_e32 v64, v64
	v_exp_f32_e32 v65, v65
	v_exp_f32_e32 v66, v66
	v_mfma_f32_32x32x16_bf16 v[32:47], v[124:127], v[148:151], v[32:47]
	ds_read_b128 v[124:127], v197 offset:40480
	v_add_f32_e32 v238, v64, v238
	v_exp_f32_e32 v67, v67
	v_add_f32_e32 v239, v65, v239
	v_exp_f32_e32 v68, v68
	v_add_f32_e32 v238, v66, v238
	v_mfma_f32_32x32x16_bf16 v[48:63], v[96:99], v[152:155], v[48:63]
	ds_read_b128 v[96:99], v197 offset:35904
	v_exp_f32_e32 v69, v69
	v_add_f32_e32 v239, v67, v239
	v_exp_f32_e32 v70, v70
	v_add_f32_e32 v238, v68, v238
	v_mfma_f32_32x32x16_bf16 v[32:47], v[100:103], v[152:155], v[32:47]
	ds_read_b128 v[100:103], v197 offset:40512
	v_exp_f32_e32 v71, v71
	v_add_f32_e32 v239, v69, v239
	v_cvt_pk_bf16_f32 v64, v64, v65
	v_add_f32_e32 v238, v70, v238
	v_mfma_f32_32x32x16_bf16 v[48:63], v[104:107], v[156:159], v[48:63]
	ds_read_b128 v[104:107], v197 offset:35936
	v_cvt_pk_bf16_f32 v65, v66, v67
	v_add_f32_e32 v239, v71, v239
	v_cvt_pk_bf16_f32 v66, v68, v69
	v_cvt_pk_bf16_f32 v67, v70, v71
	v_mfma_f32_32x32x16_bf16 v[32:47], v[108:111], v[156:159], v[32:47]
	ds_read_b128 v[108:111], v197 offset:40544
	v_exp_f32_e32 v72, v72
	v_exp_f32_e32 v73, v73
	v_exp_f32_e32 v74, v74
	v_add_f32_e32 v238, v72, v238
	s_waitcnt lgkmcnt(7)
	v_mfma_f32_32x32x16_bf16 v[16:31], v[112:115], v[80:83], v[16:31]
	ds_read_b128 v[112:115], v236 offset:13376
	v_exp_f32_e32 v75, v75
	v_add_f32_e32 v239, v73, v239
	v_exp_f32_e32 v76, v76
	v_add_f32_e32 v238, v74, v238
	s_waitcnt lgkmcnt(7)
	v_mfma_f32_32x32x16_bf16 v[0:15], v[116:119], v[80:83], v[0:15]
	ds_read_b128 v[116:119], v236 offset:20032
	v_exp_f32_e32 v77, v77
	v_add_f32_e32 v239, v75, v239
	v_exp_f32_e32 v78, v78
	v_add_f32_e32 v238, v76, v238
	s_waitcnt lgkmcnt(7)
	v_mfma_f32_32x32x16_bf16 v[16:31], v[120:123], v[88:91], v[16:31]
	ds_read_b128 v[120:123], v236 offset:13408
	v_exp_f32_e32 v79, v79
	v_add_f32_e32 v239, v77, v239
	v_cvt_pk_bf16_f32 v72, v72, v73
	v_add_f32_e32 v238, v78, v238
	s_waitcnt lgkmcnt(7)
	v_mfma_f32_32x32x16_bf16 v[0:15], v[124:127], v[88:91], v[0:15]
	ds_read_b128 v[124:127], v236 offset:20064
	v_cvt_pk_bf16_f32 v73, v74, v75
	v_add_f32_e32 v239, v79, v239
	v_cvt_pk_bf16_f32 v74, v76, v77
	v_cvt_pk_bf16_f32 v75, v78, v79
	s_waitcnt lgkmcnt(7)
	v_mfma_f32_32x32x16_bf16 v[16:31], v[96:99], v[64:67], v[16:31]
	ds_read_b128 v[96:99], v236 offset:13312
	v_max3_f32 v240, v48, v32, v49
	v_max3_f32 v241, v33, v50, v34
	v_max3_f32 v240, v51, v35, v240
	v_max3_f32 v241, v52, v36, v241
	s_waitcnt lgkmcnt(7)
	v_mfma_f32_32x32x16_bf16 v[0:15], v[100:103], v[64:67], v[0:15]
	ds_read_b128 v[100:103], v236 offset:19968
	v_max3_f32 v240, v53, v37, v240
	v_max3_f32 v241, v54, v38, v241
	v_max3_f32 v240, v55, v39, v240
	v_max3_f32 v241, v56, v40, v241
	s_waitcnt lgkmcnt(7)
	v_mfma_f32_32x32x16_bf16 v[16:31], v[104:107], v[72:75], v[16:31]
	ds_read_b128 v[104:107], v236 offset:13344
	v_max3_f32 v240, v57, v41, v240
	v_max3_f32 v241, v58, v42, v241
	v_max3_f32 v240, v59, v43, v240
	v_max3_f32 v241, v60, v44, v241
	s_waitcnt lgkmcnt(7)
	v_mfma_f32_32x32x16_bf16 v[0:15], v[108:111], v[72:75], v[0:15]
	ds_read_b128 v[108:111], v236 offset:20000
	v_max3_f32 v240, v61, v45, v240
	v_max3_f32 v241, v62, v46, v241
	v_max3_f32 v240, v63, v47, v240
	v_max_f32_e32 v240, v240, v241
	v_lshl_add_u64 v[130:131], v[130:131], 0, s[84:85]
	v_lshl_add_u64 v[220:221], v[220:221], 0, s[84:85]
	s_mov_b32 s0, s31
	s_add_i32 s31, s31, 2
	s_cmp_lt_u32 s0, s19
	s_cbranch_scc1 .Lmf_top
	s_branch .Lm_fold

; #define MFMA(a, b, c) __builtin_amdgcn_mfma_f32_32x32x16_bf16((a), (b), (c), 0, 0, 0)
; DI unsigned pack2(float a, float b) { f32x2v f = {a, b}; bf16x2v v = __builtin_convertvector(f, bf16x2v); return __builtin_bit_cast(unsigned, v); }
; DI float xhalf(float v) { return __shfl_xor(v, 32); }
;   template <int PAR>
;   DI void step(int t, f32x16 (&cur)[2], f32x16 (&nxt)[2]) {
;     if (t + 1 < nt) sstore_k(PAR ^ 1);
;     if (t > 0) sstore_v(PAR);
;     __syncthreads();
;     if (t + 1 < nt) qk(PAR ^ 1, nxt);
;     float mx = fmaxf(cur[0][0], cur[1][0]);
; #pragma unroll
;     for (int i = 1; i < 16; ++i) mx = fmaxf(fmaxf(cur[0][i], cur[1][i]), mx);
;     if (__builtin_amdgcn_ballot_w64(mx > ATT_THR) != 0ull) {
;       asm volatile("" ::: "memory");
;       mx = fmaxf(mx, xhalf(mx));
;       const float want = mref + fmaxf(mx, 0.f);
;       const float mn = __uint_as_float(pack2(want, 0.f) << 16);
;       const float d = mn - mref;
;       const float alpha = __builtin_amdgcn_exp2f(-d);
;       mref = mn;
;       l *= alpha;
; #pragma unroll
;       for (int a = 0; a < 2; ++a)
; #pragma unroll
;         for (int i = 0; i < 16; ++i) { o[a][i] *= alpha; cur[a][i] -= d; nxt[a][i] -= d; }
;       u32x4 q4 = {h == 0 ? (pack2(-mn, 0.f) & 0xffffu) : 0u, 0u, 0u, 0u};
;       qm = __builtin_bit_cast(bf16x8, q4);
;     }
;     float psum = 0.f;
; #pragma unroll
;     for (int kb2 = 0; kb2 < 2; ++kb2)
; #pragma unroll
;       for (int i = 0; i < 16; ++i) { const float pv = __builtin_amdgcn_exp2f(cur[kb2][i]); cur[kb2][i] = pv; psum += pv; }
;     l += psum;
;     if (t + 2 < nt) gload_k(t + 2);
;     if (t + 1 < nt) gload_v(t + 1);
;     const u16* vb = sV + PAR * VBUF + r * GP + h * 8;
; #pragma unroll
;     for (int kb2 = 0; kb2 < 2; ++kb2)
; #pragma unroll
;       for (int s2 = 0; s2 < 2; ++s2) {
;         u32x4 pk = {pack2(cur[kb2][8 * s2], cur[kb2][8 * s2 + 1]), pack2(cur[kb2][8 * s2 + 2], cur[kb2][8 * s2 + 3]),
;                     pack2(cur[kb2][8 * s2 + 4], cur[kb2][8 * s2 + 5]), pack2(cur[kb2][8 * s2 + 6], cur[kb2][8 * s2 + 7])};
;         const bf16x8 pf = __builtin_bit_cast(bf16x8, pk);
; #pragma unroll
;         for (int db = 0; db < 2; ++db) {
;           const bf16x8 a = *(const bf16x8*)(vb + db * 32 * GP + kb2 * 32 + s2 * 16);
;           o[db] = MFMA(a, pf, o[db]);
;         }
;       }
.Lm_skipKA:
	global_load_dwordx4 v[172:175], v[130:131], off offset:-128
	global_load_dwordx4 v[176:179], v[220:221], off offset:-128
	v_exp_f32_e32 v48, v48
	v_exp_f32_e32 v49, v49
	v_exp_f32_e32 v50, v50
	v_add_f32_e32 v238, v48, v238
	v_exp_f32_e32 v51, v51
	v_add_f32_e32 v239, v49, v239
	v_exp_f32_e32 v52, v52
	v_add_f32_e32 v238, v50, v238
	s_waitcnt lgkmcnt(8)
	v_mfma_f32_32x32x16_bf16 v[80:95], v[96:99], v[136:139], 0
	ds_read_b128 v[96:99], v236 offset:13440
	v_exp_f32_e32 v53, v53
	v_add_f32_e32 v239, v51, v239
	v_exp_f32_e32 v54, v54
	v_add_f32_e32 v238, v52, v238
	s_waitcnt lgkmcnt(8)
	v_mfma_f32_32x32x16_bf16 v[64:79], v[100:103], v[136:139], 0
	ds_read_b128 v[100:103], v236 offset:20096
	v_exp_f32_e32 v55, v55
	v_add_f32_e32 v239, v53, v239
	v_cvt_pk_bf16_f32 v48, v48, v49
	v_add_f32_e32 v238, v54, v238
	s_waitcnt lgkmcnt(8)
	v_mfma_f32_32x32x16_bf16 v[80:95], v[104:107], v[140:143], v[80:95]
	ds_read_b128 v[104:107], v236 offset:13472
	v_cvt_pk_bf16_f32 v49, v50, v51
	v_add_f32_e32 v239, v55, v239
	v_cvt_pk_bf16_f32 v50, v52, v53
	v_cvt_pk_bf16_f32 v51, v54, v55
	s_waitcnt lgkmcnt(8)
	v_mfma_f32_32x32x16_bf16 v[64:79], v[108:111], v[140:143], v[64:79]
	ds_read_b128 v[108:111], v236 offset:20128
	v_exp_f32_e32 v56, v56
	v_exp_f32_e32 v57, v57
	v_exp_f32_e32 v58, v58
	v_add_f32_e32 v238, v56, v238
	s_waitcnt lgkmcnt(0)
	s_barrier
	v_mfma_f32_32x32x16_bf16 v[80:95], v[112:115], v[144:147], v[80:95]
	ds_read_b128 v[112:115], v197 offset:26624
	v_exp_f32_e32 v59, v59
	v_add_f32_e32 v239, v57, v239
	v_exp_f32_e32 v60, v60
	v_add_f32_e32 v238, v58, v238
	v_mfma_f32_32x32x16_bf16 v[64:79], v[116:119], v[144:147], v[64:79]
	ds_read_b128 v[116:119], v197 offset:31232
	v_exp_f32_e32 v61, v61
	v_add_f32_e32 v239, v59, v239
	v_exp_f32_e32 v62, v62
	v_add_f32_e32 v238, v60, v238
	v_mfma_f32_32x32x16_bf16 v[80:95], v[120:123], v[148:151], v[80:95]
	ds_read_b128 v[120:123], v197 offset:26656
	v_exp_f32_e32 v63, v63
	v_add_f32_e32 v239, v61, v239
	v_cvt_pk_bf16_f32 v56, v56, v57
	v_add_f32_e32 v238, v62, v238
	v_mfma_f32_32x32x16_bf16 v[64:79], v[124:127], v[148:151], v[64:79]
	ds_read_b128 v[124:127], v197 offset:31264
	v_cvt_pk_bf16_f32 v57, v58, v59
	v_add_f32_e32 v239, v63, v239
	v_cvt_pk_bf16_f32 v58, v60, v61
	v_cvt_pk_bf16_f32 v59, v62, v63
	v_mfma_f32_32x32x16_bf16 v[80:95], v[96:99], v[152:155], v[80:95]
	ds_read_b128 v[96:99], v197 offset:26688
	v_exp_f32_e32 v32, v32
	v_exp_f32_e32 v33, v33
	v_exp_f32_e32 v34, v34
	v_add_f32_e32 v238, v32, v238
	v_mfma_f32_32x32x16_bf16 v[64:79], v[100:103], v[152:155], v[64:79]
	ds_read_b128 v[100:103], v197 offset:31296
	v_exp_f32_e32 v35, v35
	v_add_f32_e32 v239, v33, v239
	v_exp_f32_e32 v36, v36
	v_add_f32_e32 v238, v34, v238
	v_mfma_f32_32x32x16_bf16 v[80:95], v[104:107], v[156:159], v[80:95]
	ds_read_b128 v[104:107], v197 offset:26720
	v_exp_f32_e32 v37, v37
	v_add_f32_e32 v239, v35, v239
	v_exp_f32_e32 v38, v38
	v_add_f32_e32 v238, v36, v238
	v_mfma_f32_32x32x16_bf16 v[64:79], v[108:111], v[156:159], v[64:79]
	ds_read_b128 v[108:111], v197 offset:31328
	v_exp_f32_e32 v39, v39
	v_add_f32_e32 v239, v37, v239
	v_cvt_pk_bf16_f32 v32, v32, v33
	v_add_f32_e32 v238, v38, v238
	v_mfma_f32_32x32x16_bf16 v[80:95], v[132:135], v[180:183], v[80:95]
	v_cvt_pk_bf16_f32 v33, v34, v35
	v_add_f32_e32 v239, v39, v239
	v_cvt_pk_bf16_f32 v34, v36, v37
	v_cvt_pk_bf16_f32 v35, v38, v39
	v_mfma_f32_32x32x16_bf16 v[64:79], v[132:135], v[180:183], v[64:79]
	v_exp_f32_e32 v40, v40
	v_exp_f32_e32 v41, v41
	v_exp_f32_e32 v42, v42
	v_add_f32_e32 v238, v40, v238
	s_waitcnt lgkmcnt(7)
	v_mfma_f32_32x32x16_bf16 v[16:31], v[112:115], v[48:51], v[16:31]
	ds_read_b128 v[112:115], v236 offset:64
	v_exp_f32_e32 v43, v43
	v_add_f32_e32 v239, v41, v239
	v_exp_f32_e32 v44, v44
	v_add_f32_e32 v238, v42, v238
	s_waitcnt lgkmcnt(7)
	v_mfma_f32_32x32x16_bf16 v[0:15], v[116:119], v[48:51], v[0:15]
	ds_read_b128 v[116:119], v236 offset:6720
	v_exp_f32_e32 v45, v45
	v_add_f32_e32 v239, v43, v239
	v_exp_f32_e32 v46, v46
	v_add_f32_e32 v238, v44, v238
	s_waitcnt lgkmcnt(7)
	v_mfma_f32_32x32x16_bf16 v[16:31], v[120:123], v[56:59], v[16:31]
	ds_read_b128 v[120:123], v236 offset:96
	v_exp_f32_e32 v47, v47
	v_add_f32_e32 v239, v45, v239
	v_cvt_pk_bf16_f32 v40, v40, v41
	v_add_f32_e32 v238, v46, v238
	s_waitcnt lgkmcnt(7)
	v_mfma_f32_32x32x16_bf16 v[0:15], v[124:127], v[56:59], v[0:15]
	ds_read_b128 v[124:127], v236 offset:6752
	v_cvt_pk_bf16_f32 v41, v42, v43
	v_add_f32_e32 v239, v47, v239
	v_cvt_pk_bf16_f32 v42, v44, v45
	v_cvt_pk_bf16_f32 v43, v46, v47
	s_waitcnt lgkmcnt(7)
	v_mfma_f32_32x32x16_bf16 v[16:31], v[96:99], v[32:35], v[16:31]
	ds_read_b128 v[96:99], v236
	v_max3_f32 v240, v80, v64, v81
	v_max3_f32 v241, v65, v82, v66
	v_max3_f32 v240, v83, v67, v240
	v_max3_f32 v241, v84, v68, v241
	s_waitcnt lgkmcnt(7)
	v_mfma_f32_32x32x16_bf16 v[0:15], v[100:103], v[32:35], v[0:15]
	ds_read_b128 v[100:103], v236 offset:6656
	v_max3_f32 v240, v85, v69, v240
	v_max3_f32 v241, v86, v70, v241
	v_max3_f32 v240, v87, v71, v240
	v_max3_f32 v241, v88, v72, v241
	s_waitcnt lgkmcnt(7)
	v_mfma_f32_32x32x16_bf16 v[16:31], v[104:107], v[40:43], v[16:31]
	ds_read_b128 v[104:107], v236 offset:32
	v_max3_f32 v240, v89, v73, v240
	v_max3_f32 v241, v90, v74, v241
	v_max3_f32 v240, v91, v75, v240
	v_max3_f32 v241, v92, v76, v241
	s_waitcnt lgkmcnt(7)
	v_mfma_f32_32x32x16_bf16 v[0:15], v[108:111], v[40:43], v[0:15]
	ds_read_b128 v[108:111], v236 offset:6688
	v_max3_f32 v240, v93, v77, v240
	v_max3_f32 v241, v94, v78, v241
	v_max3_f32 v240, v95, v79, v240
	v_max_f32_e32 v240, v240, v241
	s_waitcnt vmcnt(0)
	ds_write_b128 v250, v[160:163] offset:13312
	ds_write_b128 v251, v[164:167] offset:13312
	ds_write_b128 v252, v[168:171] offset:13312
	ds_write_b128 v194, v[172:175] offset:35840
	ds_write_b128 v196, v[176:179] offset:35840
	v_cmp_lt_f32_e32 vcc, s65, v240
	s_cbranch_vccnz .Lm_rareB

; #define MFMA(a, b, c) __builtin_amdgcn_mfma_f32_32x32x16_bf16((a), (b), (c), 0, 0, 0)
; DI unsigned pack2(float a, float b) { f32x2v f = {a, b}; bf16x2v v = __builtin_convertvector(f, bf16x2v); return __builtin_bit_cast(unsigned, v); }
;   DI void qk(int buf, f32x16 (&s)[2]) {
;     const u16* kb = sK + buf * KBUF + sr * KP + h * 8;
; #pragma unroll
;     for (int kb2 = 0; kb2 < 2; ++kb2)
; #pragma unroll
;       for (int i = 0; i < 16; ++i) s[kb2][i] = 0.f;
; #pragma unroll
;     for (int ks = 0; ks < NKS; ++ks)
; #pragma unroll
;       for (int kb2 = 0; kb2 < 2; ++kb2) {
;         const bf16x8 a = *(const bf16x8*)(kb + kb2 * 32 * KP + ks * 16);
;         s[kb2] = MFMA(a, qf[ks], s[kb2]);
;       }
;     s[0] = MFMA(kone, qm, s[0]);
;     s[1] = MFMA(kone, qm, s[1]);
;   template <int PAR>
;   DI void step(int t, f32x16 (&cur)[2], f32x16 (&nxt)[2]) {
;     ...
;     float psum = 0.f;
; #pragma unroll
;     for (int kb2 = 0; kb2 < 2; ++kb2)
; #pragma unroll
;       for (int i = 0; i < 16; ++i) { const float pv = __builtin_amdgcn_exp2f(cur[kb2][i]); cur[kb2][i] = pv; psum += pv; }
;     l += psum;
;     if (t + 2 < nt) gload_k(t + 2);
;     if (t + 1 < nt) gload_v(t + 1);
;     const u16* vb = sV + PAR * VBUF + r * GP + h * 8;
; #pragma unroll
;     for (int kb2 = 0; kb2 < 2; ++kb2)
; #pragma unroll
;       for (int s2 = 0; s2 < 2; ++s2) {
;         u32x4 pk = {pack2(cur[kb2][8 * s2], cur[kb2][8 * s2 + 1]), pack2(cur[kb2][8 * s2 + 2], cur[kb2][8 * s2 + 3]),
;                     pack2(cur[kb2][8 * s2 + 4], cur[kb2][8 * s2 + 5]), pack2(cur[kb2][8 * s2 + 6], cur[kb2][8 * s2 + 7])};
;         const bf16x8 pf = __builtin_bit_cast(bf16x8, pk);
; #pragma unroll
;         for (int db = 0; db < 2; ++db) {
;           const bf16x8 a = *(const bf16x8*)(vb + db * 32 * GP + kb2 * 32 + s2 * 16);
;           o[db] = MFMA(a, pf, o[db]);
;         }
;       }
.Lm_skipVB:
	v_exp_f32_e32 v80, v80
	v_exp_f32_e32 v81, v81
	v_exp_f32_e32 v82, v82
	v_add_f32_e32 v238, v80, v238
	v_exp_f32_e32 v83, v83
	v_add_f32_e32 v239, v81, v239
	v_exp_f32_e32 v84, v84
	v_add_f32_e32 v238, v82, v238
	s_waitcnt lgkmcnt(8)
	v_mfma_f32_32x32x16_bf16 v[48:63], v[96:99], v[136:139], 0
	ds_read_b128 v[96:99], v236 offset:128
	v_exp_f32_e32 v85, v85
	v_add_f32_e32 v239, v83, v239
	v_exp_f32_e32 v86, v86
	v_add_f32_e32 v238, v84, v238
	s_waitcnt lgkmcnt(8)
	v_mfma_f32_32x32x16_bf16 v[32:47], v[100:103], v[136:139], 0
	ds_read_b128 v[100:103], v236 offset:6784
	v_exp_f32_e32 v87, v87
	v_add_f32_e32 v239, v85, v239
	v_cvt_pk_bf16_f32 v80, v80, v81
	v_add_f32_e32 v238, v86, v238
	s_waitcnt lgkmcnt(8)
	v_mfma_f32_32x32x16_bf16 v[48:63], v[104:107], v[140:143], v[48:63]
	ds_read_b128 v[104:107], v236 offset:160
	v_cvt_pk_bf16_f32 v81, v82, v83
	v_add_f32_e32 v239, v87, v239
	v_cvt_pk_bf16_f32 v82, v84, v85
	v_cvt_pk_bf16_f32 v83, v86, v87
	s_waitcnt lgkmcnt(8)
	v_mfma_f32_32x32x16_bf16 v[32:47], v[108:111], v[140:143], v[32:47]
	ds_read_b128 v[108:111], v236 offset:6816
	v_exp_f32_e32 v88, v88
	v_exp_f32_e32 v89, v89
	v_exp_f32_e32 v90, v90
	v_add_f32_e32 v238, v88, v238
	s_waitcnt lgkmcnt(0)
	s_barrier
	v_mfma_f32_32x32x16_bf16 v[48:63], v[112:115], v[144:147], v[48:63]
	ds_read_b128 v[112:115], v197 offset:35840
	v_exp_f32_e32 v91, v91
	v_add_f32_e32 v239, v89, v239
	v_exp_f32_e32 v92, v92
	v_add_f32_e32 v238, v90, v238
	v_mfma_f32_32x32x16_bf16 v[32:47], v[116:119], v[144:147], v[32:47]
	ds_read_b128 v[116:119], v197 offset:40448
	v_exp_f32_e32 v93, v93
	v_add_f32_e32 v239, v91, v239
	v_exp_f32_e32 v94, v94
	v_add_f32_e32 v238, v92, v238
	v_mfma_f32_32x32x16_bf16 v[48:63], v[120:123], v[148:151], v[48:63]
	ds_read_b128 v[120:123], v197 offset:35872
	v_exp_f32_e32 v95, v95
	v_add_f32_e32 v239, v93, v239
	v_cvt_pk_bf16_f32 v88, v88, v89
	v_add_f32_e32 v238, v94, v238
	v_mfma_f32_32x32x16_bf16 v[32:47], v[124:127], v[148:151], v[32:47]
	ds_read_b128 v[124:127], v197 offset:40480
	v_cvt_pk_bf16_f32 v89, v90, v91
	v_add_f32_e32 v239, v95, v239
	v_cvt_pk_bf16_f32 v90, v92, v93
	v_cvt_pk_bf16_f32 v91, v94, v95
	v_mfma_f32_32x32x16_bf16 v[48:63], v[96:99], v[152:155], v[48:63]
	ds_read_b128 v[96:99], v197 offset:35904
	v_exp_f32_e32 v64, v64
	v_exp_f32_e32 v65, v65
	v_exp_f32_e32 v66, v66
	v_add_f32_e32 v238, v64, v238
	v_mfma_f32_32x32x16_bf16 v[32:47], v[100:103], v[152:155], v[32:47]
	ds_read_b128 v[100:103], v197 offset:40512
	v_exp_f32_e32 v67, v67
	v_add_f32_e32 v239, v65, v239
	v_exp_f32_e32 v68, v68
	v_add_f32_e32 v238, v66, v238
	v_mfma_f32_32x32x16_bf16 v[48:63], v[104:107], v[156:159], v[48:63]
	ds_read_b128 v[104:107], v197 offset:35936
	v_exp_f32_e32 v69, v69
	v_add_f32_e32 v239, v67, v239
	v_exp_f32_e32 v70, v70
	v_add_f32_e32 v238, v68, v238
	v_mfma_f32_32x32x16_bf16 v[32:47], v[108:111], v[156:159], v[32:47]
	ds_read_b128 v[108:111], v197 offset:40544
	v_exp_f32_e32 v71, v71
	v_add_f32_e32 v239, v69, v239
	v_cvt_pk_bf16_f32 v64, v64, v65
	v_add_f32_e32 v238, v70, v238
	v_mfma_f32_32x32x16_bf16 v[48:63], v[132:135], v[180:183], v[48:63]
	v_cvt_pk_bf16_f32 v65, v66, v67
	v_add_f32_e32 v239, v71, v239
	v_cvt_pk_bf16_f32 v66, v68, v69
	v_cvt_pk_bf16_f32 v67, v70, v71
	v_mfma_f32_32x32x16_bf16 v[32:47], v[132:135], v[180:183], v[32:47]
	v_exp_f32_e32 v72, v72
	v_exp_f32_e32 v73, v73
	v_exp_f32_e32 v74, v74
	v_add_f32_e32 v238, v72, v238
	s_waitcnt lgkmcnt(7)
	v_mfma_f32_32x32x16_bf16 v[16:31], v[112:115], v[80:83], v[16:31]
	ds_read_b128 v[112:115], v236 offset:13376
	v_exp_f32_e32 v75, v75
	v_add_f32_e32 v239, v73, v239
	v_exp_f32_e32 v76, v76
	v_add_f32_e32 v238, v74, v238
	s_waitcnt lgkmcnt(7)
	v_mfma_f32_32x32x16_bf16 v[0:15], v[116:119], v[80:83], v[0:15]
	ds_read_b128 v[116:119], v236 offset:20032
	v_exp_f32_e32 v77, v77
	v_add_f32_e32 v239, v75, v239
	v_exp_f32_e32 v78, v78
	v_add_f32_e32 v238, v76, v238
	s_waitcnt lgkmcnt(7)
	v_mfma_f32_32x32x16_bf16 v[16:31], v[120:123], v[88:91], v[16:31]
	ds_read_b128 v[120:123], v236 offset:13408
	v_exp_f32_e32 v79, v79
	v_add_f32_e32 v239, v77, v239
	v_cvt_pk_bf16_f32 v72, v72, v73
	v_add_f32_e32 v238, v78, v238
	s_waitcnt lgkmcnt(7)
	v_mfma_f32_32x32x16_bf16 v[0:15], v[124:127], v[88:91], v[0:15]
	ds_read_b128 v[124:127], v236 offset:20064
	v_cvt_pk_bf16_f32 v73, v74, v75
	v_add_f32_e32 v239, v79, v239
	v_cvt_pk_bf16_f32 v74, v76, v77
	v_cvt_pk_bf16_f32 v75, v78, v79
	s_waitcnt lgkmcnt(7)
	v_mfma_f32_32x32x16_bf16 v[16:31], v[96:99], v[64:67], v[16:31]
	ds_read_b128 v[96:99], v236 offset:13312
	v_max3_f32 v240, v48, v32, v49
	v_max3_f32 v241, v33, v50, v34
	v_max3_f32 v240, v51, v35, v240
	v_max3_f32 v241, v52, v36, v241
	s_waitcnt lgkmcnt(7)
	v_mfma_f32_32x32x16_bf16 v[0:15], v[100:103], v[64:67], v[0:15]
	ds_read_b128 v[100:103], v236 offset:19968
	v_max3_f32 v240, v53, v37, v240
	v_max3_f32 v241, v54, v38, v241
	v_max3_f32 v240, v55, v39, v240
	v_max3_f32 v241, v56, v40, v241
	s_waitcnt lgkmcnt(7)
	v_mfma_f32_32x32x16_bf16 v[16:31], v[104:107], v[72:75], v[16:31]
	ds_read_b128 v[104:107], v236 offset:13344
	v_max3_f32 v240, v57, v41, v240
	v_max3_f32 v241, v58, v42, v241
	v_max3_f32 v240, v59, v43, v240
	v_max3_f32 v241, v60, v44, v241
	s_waitcnt lgkmcnt(7)
	v_mfma_f32_32x32x16_bf16 v[0:15], v[108:111], v[72:75], v[0:15]
	ds_read_b128 v[108:111], v236 offset:20000
	v_max3_f32 v240, v61, v45, v240
	v_max3_f32 v241, v62, v46, v241
	v_max3_f32 v240, v63, v47, v240
	v_max_f32_e32 v240, v240, v241
	v_lshl_add_u64 v[130:131], v[130:131], 0, s[84:85]
	v_lshl_add_u64 v[220:221], v[220:221], 0, s[84:85]
	s_mov_b32 s0, s31
	s_add_i32 s31, s31, 2
	s_cmp_lt_u32 s0, s19
	s_cbranch_scc1 .LBB0_268
	s_branch .Lm_fold
; DI unsigned pack2(float a, float b) { f32x2v f = {a, b}; bf16x2v v = __builtin_convertvector(f, bf16x2v); return __builtin_bit_cast(unsigned, v); }
; DI float xhalf(float v) { return __shfl_xor(v, 32); }
;   template <int PAR>
;   DI void step(int t, f32x16 (&cur)[2], f32x16 (&nxt)[2]) {
;     ...
;     if (__builtin_amdgcn_ballot_w64(mx > ATT_THR) != 0ull) {
;       asm volatile("" ::: "memory");
;       mx = fmaxf(mx, xhalf(mx));
;       const float want = mref + fmaxf(mx, 0.f);
;       const float mn = __uint_as_float(pack2(want, 0.f) << 16);
;       const float d = mn - mref;
;       const float alpha = __builtin_amdgcn_exp2f(-d);
;       mref = mn;
;       l *= alpha;
; #pragma unroll
;       for (int a = 0; a < 2; ++a)
; #pragma unroll
;         for (int i = 0; i < 16; ++i) { o[a][i] *= alpha; cur[a][i] -= d; nxt[a][i] -= d; }
;       u32x4 q4 = {h == 0 ? (pack2(-mn, 0.f) & 0xffffu) : 0u, 0u, 0u, 0u};
;       qm = __builtin_bit_cast(bf16x8, q4);
;     }
;     float psum = 0.f;
; #pragma unroll
;     for (int kb2 = 0; kb2 < 2; ++kb2)
; #pragma unroll
;       for (int i = 0; i < 16; ++i) { const float pv = __builtin_amdgcn_exp2f(cur[kb2][i]); cur[kb2][i] = pv; psum += pv; }
;     l += psum;
.Lm_fold:
	s_waitcnt lgkmcnt(0)
	v_add_f32_e32 v237, v237, v238
	v_add_f32_e32 v237, v237, v239
	s_branch .LBB0_283
.Lmf_rareA:
	v_cmp_lt_i32_e64 s[0:1], v229, v228
	s_nop 1
	v_cndmask_b32_e64 v241, v227, v229, s[0:1]
	v_lshlrev_b32_e32 v241, 2, v241
	ds_bpermute_b32 v241, v241, v240
	s_waitcnt lgkmcnt(0)
	v_max3_f32 v240, v240, v241, 0
	v_add_f32_e32 v240, v218, v240
	v_cvt_pk_bf16_f32 v240, v240, 0
	v_lshlrev_b32_e32 v241, 16, v240
	v_sub_f32_e32 v240, v241, v218
	v_exp_f32_e64 v181, -v240
	v_sub_f32_e32 v48, v48, v240
	v_sub_f32_e32 v49, v49, v240
	v_sub_f32_e32 v50, v50, v240
	v_sub_f32_e32 v51, v51, v240
	v_sub_f32_e32 v52, v52, v240
	v_sub_f32_e32 v53, v53, v240
	v_sub_f32_e32 v54, v54, v240
	v_sub_f32_e32 v55, v55, v240
	v_sub_f32_e32 v56, v56, v240
	v_sub_f32_e32 v57, v57, v240
	v_sub_f32_e32 v58, v58, v240
	v_sub_f32_e32 v59, v59, v240
	v_sub_f32_e32 v60, v60, v240
	v_sub_f32_e32 v61, v61, v240
	v_sub_f32_e32 v62, v62, v240
	v_sub_f32_e32 v63, v63, v240
	v_sub_f32_e32 v32, v32, v240
	v_sub_f32_e32 v33, v33, v240
	v_sub_f32_e32 v34, v34, v240
	v_sub_f32_e32 v35, v35, v240
	v_sub_f32_e32 v36, v36, v240
	v_sub_f32_e32 v37, v37, v240
	v_sub_f32_e32 v38, v38, v240
	v_sub_f32_e32 v39, v39, v240
	v_sub_f32_e32 v40, v40, v240
	v_sub_f32_e32 v41, v41, v240
	v_sub_f32_e32 v42, v42, v240
	v_sub_f32_e32 v43, v43, v240
	v_sub_f32_e32 v44, v44, v240
	v_sub_f32_e32 v45, v45, v240
	v_sub_f32_e32 v46, v46, v240
	v_sub_f32_e32 v47, v47, v240
	v_xor_b32_e32 v240, 0x80000000, v241
	v_cvt_pk_bf16_f32 v240, v240, 0
	v_and_b32_e32 v240, 0xffff, v240
	v_mul_f32_e32 v237, v237, v181
	v_mul_f32_e32 v238, v238, v181
	v_mul_f32_e32 v239, v239, v181
	v_mul_f32_e32 v0, v0, v181
	v_mul_f32_e32 v1, v1, v181
	v_mul_f32_e32 v2, v2, v181
	v_mul_f32_e32 v3, v3, v181
	v_mul_f32_e32 v4, v4, v181
	v_mul_f32_e32 v5, v5, v181
	v_mul_f32_e32 v6, v6, v181
	v_mul_f32_e32 v7, v7, v181
	v_mul_f32_e32 v8, v8, v181
	v_mul_f32_e32 v9, v9, v181
	v_mul_f32_e32 v10, v10, v181
	v_mul_f32_e32 v11, v11, v181
	v_mul_f32_e32 v12, v12, v181
	v_mul_f32_e32 v13, v13, v181
	v_mul_f32_e32 v14, v14, v181
	v_mul_f32_e32 v15, v15, v181
	v_mul_f32_e32 v16, v16, v181
	v_mul_f32_e32 v17, v17, v181
	v_mul_f32_e32 v18, v18, v181
	v_mul_f32_e32 v19, v19, v181
	v_mul_f32_e32 v20, v20, v181
	v_mul_f32_e32 v21, v21, v181
	v_mul_f32_e32 v22, v22, v181
	v_mul_f32_e32 v23, v23, v181
	v_mul_f32_e32 v24, v24, v181
	v_mul_f32_e32 v25, v25, v181
	v_mul_f32_e32 v26, v26, v181
	v_mul_f32_e32 v27, v27, v181
	v_mul_f32_e32 v28, v28, v181
	v_mul_f32_e32 v29, v29, v181
	v_mul_f32_e32 v30, v30, v181
	v_mul_f32_e32 v31, v31, v181
	v_cndmask_b32_e64 v180, 0, v240, s[6:7]
	v_mov_b32_e32 v218, v241
	v_mov_b32_e32 v181, 0
	s_branch .Lm_rareA_ret
.Lmf_rareB:
	v_cmp_lt_i32_e64 s[0:1], v229, v228
	s_nop 1
	v_cndmask_b32_e64 v241, v227, v229, s[0:1]
	v_lshlrev_b32_e32 v241, 2, v241
	ds_bpermute_b32 v241, v241, v240
	s_waitcnt lgkmcnt(0)
	v_max3_f32 v240, v240, v241, 0
	v_add_f32_e32 v240, v218, v240
	v_cvt_pk_bf16_f32 v240, v240, 0
	v_lshlrev_b32_e32 v241, 16, v240
	v_sub_f32_e32 v240, v241, v218
	v_exp_f32_e64 v181, -v240
	v_sub_f32_e32 v80, v80, v240
	v_sub_f32_e32 v81, v81, v240
	v_sub_f32_e32 v82, v82, v240
	v_sub_f32_e32 v83, v83, v240
	v_sub_f32_e32 v84, v84, v240
	v_sub_f32_e32 v85, v85, v240
	v_sub_f32_e32 v86, v86, v240
	v_sub_f32_e32 v87, v87, v240
	v_sub_f32_e32 v88, v88, v240
	v_sub_f32_e32 v89, v89, v240
	v_sub_f32_e32 v90, v90, v240
	v_sub_f32_e32 v91, v91, v240
	v_sub_f32_e32 v92, v92, v240
	v_sub_f32_e32 v93, v93, v240
	v_sub_f32_e32 v94, v94, v240
	v_sub_f32_e32 v95, v95, v240
	v_sub_f32_e32 v64, v64, v240
	v_sub_f32_e32 v65, v65, v240
	v_sub_f32_e32 v66, v66, v240
	v_sub_f32_e32 v67, v67, v240
	v_sub_f32_e32 v68, v68, v240
	v_sub_f32_e32 v69, v69, v240
	v_sub_f32_e32 v70, v70, v240
	v_sub_f32_e32 v71, v71, v240
	v_sub_f32_e32 v72, v72, v240
	v_sub_f32_e32 v73, v73, v240
	v_sub_f32_e32 v74, v74, v240
	v_sub_f32_e32 v75, v75, v240
	v_sub_f32_e32 v76, v76, v240
	v_sub_f32_e32 v77, v77, v240
	v_sub_f32_e32 v78, v78, v240
	v_sub_f32_e32 v79, v79, v240
	v_xor_b32_e32 v240, 0x80000000, v241
	v_cvt_pk_bf16_f32 v240, v240, 0
	v_and_b32_e32 v240, 0xffff, v240
	v_mul_f32_e32 v237, v237, v181
	v_mul_f32_e32 v238, v238, v181
	v_mul_f32_e32 v239, v239, v181
	v_mul_f32_e32 v0, v0, v181
	v_mul_f32_e32 v1, v1, v181
	v_mul_f32_e32 v2, v2, v181
	v_mul_f32_e32 v3, v3, v181
	v_mul_f32_e32 v4, v4, v181
	v_mul_f32_e32 v5, v5, v181
	v_mul_f32_e32 v6, v6, v181
	v_mul_f32_e32 v7, v7, v181
	v_mul_f32_e32 v8, v8, v181
	v_mul_f32_e32 v9, v9, v181
	v_mul_f32_e32 v10, v10, v181
	v_mul_f32_e32 v11, v11, v181
	v_mul_f32_e32 v12, v12, v181
	v_mul_f32_e32 v13, v13, v181
	v_mul_f32_e32 v14, v14, v181
	v_mul_f32_e32 v15, v15, v181
	v_mul_f32_e32 v16, v16, v181
	v_mul_f32_e32 v17, v17, v181
	v_mul_f32_e32 v18, v18, v181
	v_mul_f32_e32 v19, v19, v181
	v_mul_f32_e32 v20, v20, v181
	v_mul_f32_e32 v21, v21, v181
	v_mul_f32_e32 v22, v22, v181
	v_mul_f32_e32 v23, v23, v181
	v_mul_f32_e32 v24, v24, v181
	v_mul_f32_e32 v25, v25, v181
	v_mul_f32_e32 v26, v26, v181
	v_mul_f32_e32 v27, v27, v181
	v_mul_f32_e32 v28, v28, v181
	v_mul_f32_e32 v29, v29, v181
	v_mul_f32_e32 v30, v30, v181
	v_mul_f32_e32 v31, v31, v181
	v_cndmask_b32_e64 v180, 0, v240, s[6:7]
	v_mov_b32_e32 v218, v241
	v_mov_b32_e32 v181, 0
	s_branch .Lm_rareB_ret
